# GEMM: s_setprio 0 ahead of the last MFMA of a segment, barrier right after it; in-projection loop also reads its phase-1 B fragments one phase early across the back edge / tile boundary (epilogue temp
# speedup vs baseline: 1.0406x; 1.0032x over previous
.LBB0_94:
	v_mov_b64_e32 v[4:5], 0x1800
	s_ashr_i32 s9, s8, 31
	v_cmp_lt_i64_e32 vcc, s[10:11], v[4:5]
	s_lshl_b64 s[10:11], s[8:9], 20
	s_add_u32 s10, s22, s10
	s_addc_u32 s11, s23, s11
	s_and_b64 s[12:13], vcc, exec
	s_cselect_b32 s9, s11, s15
	s_cselect_b32 s37, s10, s14
	s_ashr_i32 s7, s6, 31
	s_lshl_b64 s[12:13], s[6:7], 20
	s_add_u32 s12, s24, s12
	s_addc_u32 s13, s25, s13
	s_and_b64 s[18:19], vcc, exec
	s_cselect_b32 s7, s13, s17
	s_cselect_b32 s38, s12, s16
	s_add_u32 s14, s14, 0x80080
	s_addc_u32 s15, s15, 0
	s_add_u32 s39, s16, 0x100
	s_addc_u32 s40, s17, 0
	s_mov_b32 s41, -2
	v_mov_b64_e32 v[4:5], 0
	v_mov_b64_e32 v[6:7], 0
	v_mov_b64_e32 v[8:9], 0
	v_mov_b64_e32 v[10:11], 0
	v_mov_b64_e32 v[12:13], 0
	v_mov_b64_e32 v[14:15], 0
	v_mov_b64_e32 v[16:17], 0
	v_mov_b64_e32 v[18:19], 0
	v_mov_b64_e32 v[20:21], 0
	v_mov_b64_e32 v[22:23], 0
	v_mov_b64_e32 v[24:25], 0
	v_mov_b64_e32 v[26:27], 0
	v_mov_b64_e32 v[28:29], 0
	v_mov_b64_e32 v[30:31], 0
	v_mov_b64_e32 v[32:33], 0
	v_mov_b64_e32 v[34:35], 0
	v_mov_b64_e32 v[36:37], 0
	v_mov_b64_e32 v[38:39], 0
	v_mov_b64_e32 v[40:41], 0
	v_mov_b64_e32 v[42:43], 0
	v_mov_b64_e32 v[44:45], 0
	v_mov_b64_e32 v[46:47], 0
	v_mov_b64_e32 v[48:49], 0
	v_mov_b64_e32 v[50:51], 0
	v_mov_b64_e32 v[52:53], 0
	v_mov_b64_e32 v[54:55], 0
	v_mov_b64_e32 v[56:57], 0
	v_mov_b64_e32 v[58:59], 0
	v_mov_b64_e32 v[60:61], 0
	v_mov_b64_e32 v[62:63], 0
	v_mov_b64_e32 v[64:65], 0
	v_mov_b64_e32 v[66:67], 0
	v_mov_b64_e32 v[68:69], 0
	v_mov_b64_e32 v[70:71], 0
	v_mov_b64_e32 v[72:73], 0
	v_mov_b64_e32 v[74:75], 0
	v_mov_b64_e32 v[76:77], 0
	v_mov_b64_e32 v[78:79], 0
	v_mov_b64_e32 v[80:81], 0
	v_mov_b64_e32 v[82:83], 0
	v_mov_b64_e32 v[84:85], 0
	v_mov_b64_e32 v[86:87], 0
	v_mov_b64_e32 v[88:89], 0
	v_mov_b64_e32 v[90:91], 0
	v_mov_b64_e32 v[92:93], 0
	v_mov_b64_e32 v[94:95], 0
	v_mov_b64_e32 v[96:97], 0
	v_mov_b64_e32 v[98:99], 0
	v_mov_b64_e32 v[100:101], 0
	v_mov_b64_e32 v[102:103], 0
	v_mov_b64_e32 v[104:105], 0
	v_mov_b64_e32 v[106:107], 0
	v_mov_b64_e32 v[108:109], 0
	v_mov_b64_e32 v[110:111], 0
	v_mov_b64_e32 v[112:113], 0
	v_mov_b64_e32 v[114:115], 0
	v_mov_b64_e32 v[116:117], 0
	v_mov_b64_e32 v[118:119], 0
	v_mov_b64_e32 v[120:121], 0
	v_mov_b64_e32 v[122:123], 0
	v_mov_b64_e32 v[124:125], 0
	v_mov_b64_e32 v[126:127], 0
	v_mov_b64_e32 v[128:129], 0
	v_mov_b64_e32 v[130:131], 0
	v_add_u32_e32 v145, 0x10000, v142
	ds_read_b128 v[146:149], v145
	ds_read_b128 v[150:153], v145 offset:1024
	ds_read_b128 v[154:157], v145 offset:2048
	ds_read_b128 v[158:161], v145 offset:3072
.LBB0_95:
	s_add_u32 s16, s14, 0xfff80080
	s_addc_u32 s17, s15, -1
	s_add_i32 s42, 0, 0x10000
	s_cmp_eq_u32 s41, 28
	s_cselect_b32 s19, s9, s17
	s_cselect_b32 s18, s37, s16
	s_cselect_b32 s17, s7, s40
	s_cselect_b32 s16, s38, s39
	s_add_i32 m0, s27, 0xc000
	ds_read_b128 v[162:165], v144
	ds_read_b128 v[166:169], v144 offset:1024
	ds_read_b128 v[170:173], v144 offset:2048
	ds_read_b128 v[174:177], v144 offset:3072
	ds_read_b128 v[178:181], v144 offset:4096
	ds_read_b128 v[182:185], v144 offset:5120
	ds_read_b128 v[186:189], v144 offset:6144
	ds_read_b128 v[190:193], v144 offset:7168
	global_load_lds_dwordx4 v138, s[14:15]
	s_add_i32 m0, s27, 0xe000
	s_nop 0
	global_load_lds_dwordx4 v140, s[14:15]
	s_waitcnt lgkmcnt(8)
	s_setprio 1
	s_barrier
	s_waitcnt lgkmcnt(0)
	v_mfma_f32_16x16x32_bf16 v[128:131], v[146:149], v[162:165], v[128:131]
	v_mfma_f32_16x16x32_bf16 v[128:131], v[150:153], v[166:169], v[128:131]
	v_mfma_f32_16x16x32_bf16 v[120:123], v[150:153], v[174:177], v[120:123]
	v_mfma_f32_16x16x32_bf16 v[120:123], v[146:149], v[170:173], v[120:123]
	v_mfma_f32_16x16x32_bf16 v[104:107], v[146:149], v[178:181], v[104:107]
	v_mfma_f32_16x16x32_bf16 v[104:107], v[150:153], v[182:185], v[104:107]
	v_mfma_f32_16x16x32_bf16 v[88:91], v[150:153], v[190:193], v[88:91]
	v_mfma_f32_16x16x32_bf16 v[88:91], v[146:149], v[186:189], v[88:91]
	v_mfma_f32_16x16x32_bf16 v[84:87], v[154:157], v[186:189], v[84:87]
	v_mfma_f32_16x16x32_bf16 v[84:87], v[158:161], v[190:193], v[84:87]
	v_mfma_f32_16x16x32_bf16 v[100:103], v[158:161], v[182:185], v[100:103]
	v_mfma_f32_16x16x32_bf16 v[100:103], v[154:157], v[178:181], v[100:103]
	v_mfma_f32_16x16x32_bf16 v[116:119], v[154:157], v[170:173], v[116:119]
	v_mfma_f32_16x16x32_bf16 v[116:119], v[158:161], v[174:177], v[116:119]
	v_mfma_f32_16x16x32_bf16 v[124:127], v[158:161], v[166:169], v[124:127]
	s_setprio 0
	v_mfma_f32_16x16x32_bf16 v[124:127], v[154:157], v[162:165], v[124:127]
	s_barrier
	s_add_i32 s44, 0, 0x14000
	s_add_i32 s42, s42, s26
	v_add_u32_e32 v145, s44, v142
	v_lshl_add_u64 v[212:213], s[16:17], 0, v[2:3]
	s_mov_b32 m0, s42
	ds_read_b128 v[194:197], v145
	ds_read_b128 v[200:203], v145 offset:1024
	ds_read_b128 v[204:207], v145 offset:2048
	ds_read_b128 v[208:211], v145 offset:3072
	global_load_lds_dwordx4 v[212:213], off
	v_lshl_add_u64 v[214:215], s[16:17], 0, v[132:133]
	s_add_i32 m0, s42, 0x2000
	s_nop 0
	global_load_lds_dwordx4 v[214:215], off
	s_setprio 1
	s_barrier
	s_waitcnt lgkmcnt(0)
	v_mfma_f32_16x16x32_bf16 v[112:115], v[194:197], v[162:165], v[112:115]
	v_mfma_f32_16x16x32_bf16 v[112:115], v[200:203], v[166:169], v[112:115]
	v_mfma_f32_16x16x32_bf16 v[96:99], v[200:203], v[174:177], v[96:99]
	v_mfma_f32_16x16x32_bf16 v[96:99], v[194:197], v[170:173], v[96:99]
	v_mfma_f32_16x16x32_bf16 v[80:83], v[194:197], v[178:181], v[80:83]
	v_mfma_f32_16x16x32_bf16 v[80:83], v[200:203], v[182:185], v[80:83]
	v_mfma_f32_16x16x32_bf16 v[72:75], v[200:203], v[190:193], v[72:75]
	v_mfma_f32_16x16x32_bf16 v[72:75], v[194:197], v[186:189], v[72:75]
	v_mfma_f32_16x16x32_bf16 v[68:71], v[204:207], v[186:189], v[68:71]
	v_mfma_f32_16x16x32_bf16 v[68:71], v[208:211], v[190:193], v[68:71]
	v_mfma_f32_16x16x32_bf16 v[76:79], v[208:211], v[182:185], v[76:79]
	v_mfma_f32_16x16x32_bf16 v[76:79], v[204:207], v[178:181], v[76:79]
	v_mfma_f32_16x16x32_bf16 v[92:95], v[204:207], v[170:173], v[92:95]
	v_mfma_f32_16x16x32_bf16 v[92:95], v[208:211], v[174:177], v[92:95]
	v_mfma_f32_16x16x32_bf16 v[108:111], v[208:211], v[166:169], v[108:111]
	s_setprio 0
	v_mfma_f32_16x16x32_bf16 v[108:111], v[204:207], v[162:165], v[108:111]
	s_barrier
	s_mov_b32 m0, s27
	v_lshl_add_u64 v[216:217], s[18:19], 0, v[136:137]
	ds_read_b128 v[162:165], v144 offset:16384
	ds_read_b128 v[166:169], v144 offset:17408
	ds_read_b128 v[170:173], v144 offset:18432
	ds_read_b128 v[174:177], v144 offset:19456
	ds_read_b128 v[178:181], v144 offset:20480
	ds_read_b128 v[182:185], v144 offset:21504
	ds_read_b128 v[186:189], v144 offset:22528
	ds_read_b128 v[190:193], v144 offset:23552
	global_load_lds_dwordx4 v[216:217], off
	v_lshl_add_u64 v[218:219], s[18:19], 0, v[134:135]
	s_mov_b32 m0, s28
	s_nop 0
	global_load_lds_dwordx4 v[218:219], off
	s_waitcnt vmcnt(10)
	s_setprio 1
	s_barrier
	s_waitcnt lgkmcnt(0)
	v_mfma_f32_16x16x32_bf16 v[64:67], v[146:149], v[162:165], v[64:67]
	v_mfma_f32_16x16x32_bf16 v[64:67], v[150:153], v[166:169], v[64:67]
	v_mfma_f32_16x16x32_bf16 v[56:59], v[150:153], v[174:177], v[56:59]
	v_mfma_f32_16x16x32_bf16 v[56:59], v[146:149], v[170:173], v[56:59]
	v_mfma_f32_16x16x32_bf16 v[40:43], v[146:149], v[178:181], v[40:43]
	v_mfma_f32_16x16x32_bf16 v[40:43], v[150:153], v[182:185], v[40:43]
	v_mfma_f32_16x16x32_bf16 v[24:27], v[150:153], v[190:193], v[24:27]
	v_mfma_f32_16x16x32_bf16 v[24:27], v[146:149], v[186:189], v[24:27]
	v_mfma_f32_16x16x32_bf16 v[20:23], v[154:157], v[186:189], v[20:23]
	v_mfma_f32_16x16x32_bf16 v[20:23], v[158:161], v[190:193], v[20:23]
	v_mfma_f32_16x16x32_bf16 v[36:39], v[158:161], v[182:185], v[36:39]
	v_mfma_f32_16x16x32_bf16 v[36:39], v[154:157], v[178:181], v[36:39]
	v_mfma_f32_16x16x32_bf16 v[52:55], v[154:157], v[170:173], v[52:55]
	v_mfma_f32_16x16x32_bf16 v[52:55], v[158:161], v[174:177], v[52:55]
	v_mfma_f32_16x16x32_bf16 v[60:63], v[158:161], v[166:169], v[60:63]
	s_setprio 0
	v_mfma_f32_16x16x32_bf16 v[60:63], v[154:157], v[162:165], v[60:63]
	s_barrier
	s_add_u32 s42, s16, 0x20000
	s_addc_u32 s43, s17, 0
	s_add_i32 s44, s44, s26
	s_mov_b32 m0, s44
	s_nop 0
	global_load_lds_dwordx4 v2, s[42:43]
	s_add_i32 m0, s44, 0x2000
	s_nop 0
	global_load_lds_dwordx4 v132, s[42:43]
	s_add_i32 s42, 0, 0x18000
	v_add_u32_e32 v145, s42, v142
	ds_read_b128 v[146:149], v145
	ds_read_b128 v[150:153], v145 offset:1024
	ds_read_b128 v[154:157], v145 offset:2048
	ds_read_b128 v[158:161], v145 offset:3072
	s_waitcnt vmcnt(6)
	s_setprio 1
	s_barrier
	v_mfma_f32_16x16x32_bf16 v[48:51], v[194:197], v[162:165], v[48:51]
	v_mfma_f32_16x16x32_bf16 v[48:51], v[200:203], v[166:169], v[48:51]
	v_mfma_f32_16x16x32_bf16 v[32:35], v[200:203], v[174:177], v[32:35]
	v_mfma_f32_16x16x32_bf16 v[32:35], v[194:197], v[170:173], v[32:35]
	v_mfma_f32_16x16x32_bf16 v[16:19], v[194:197], v[178:181], v[16:19]
	v_mfma_f32_16x16x32_bf16 v[16:19], v[200:203], v[182:185], v[16:19]
	v_mfma_f32_16x16x32_bf16 v[8:11], v[200:203], v[190:193], v[8:11]
	v_mfma_f32_16x16x32_bf16 v[8:11], v[194:197], v[186:189], v[8:11]
	v_mfma_f32_16x16x32_bf16 v[4:7], v[204:207], v[186:189], v[4:7]
	v_mfma_f32_16x16x32_bf16 v[4:7], v[208:211], v[190:193], v[4:7]
	v_mfma_f32_16x16x32_bf16 v[12:15], v[208:211], v[182:185], v[12:15]
	v_mfma_f32_16x16x32_bf16 v[12:15], v[204:207], v[178:181], v[12:15]
	v_mfma_f32_16x16x32_bf16 v[28:31], v[204:207], v[170:173], v[28:31]
	v_mfma_f32_16x16x32_bf16 v[28:31], v[208:211], v[174:177], v[28:31]
	v_mfma_f32_16x16x32_bf16 v[44:47], v[208:211], v[166:169], v[44:47]
	s_setprio 0
	v_mfma_f32_16x16x32_bf16 v[44:47], v[204:207], v[162:165], v[44:47]
	s_barrier
	s_add_u32 s18, s18, 0x80000
	s_addc_u32 s19, s19, 0
	s_mov_b32 m0, s29
	ds_read_b128 v[162:165], v144 offset:32768
	ds_read_b128 v[166:169], v144 offset:33792
	ds_read_b128 v[170:173], v144 offset:34816
	ds_read_b128 v[174:177], v144 offset:35840
	ds_read_b128 v[178:181], v144 offset:36864
	ds_read_b128 v[182:185], v144 offset:37888
	ds_read_b128 v[186:189], v144 offset:38912
	ds_read_b128 v[190:193], v144 offset:39936
	global_load_lds_dwordx4 v136, s[18:19]
	s_mov_b32 m0, s30
	s_nop 0
	global_load_lds_dwordx4 v134, s[18:19]
	s_waitcnt lgkmcnt(8)
	s_setprio 1
	s_barrier
	s_waitcnt lgkmcnt(0)
	v_mfma_f32_16x16x32_bf16 v[128:131], v[146:149], v[162:165], v[128:131]
	v_mfma_f32_16x16x32_bf16 v[128:131], v[150:153], v[166:169], v[128:131]
	v_mfma_f32_16x16x32_bf16 v[120:123], v[150:153], v[174:177], v[120:123]
	v_mfma_f32_16x16x32_bf16 v[120:123], v[146:149], v[170:173], v[120:123]
	v_mfma_f32_16x16x32_bf16 v[104:107], v[146:149], v[178:181], v[104:107]
	v_mfma_f32_16x16x32_bf16 v[104:107], v[150:153], v[182:185], v[104:107]
	v_mfma_f32_16x16x32_bf16 v[88:91], v[150:153], v[190:193], v[88:91]
	v_mfma_f32_16x16x32_bf16 v[88:91], v[146:149], v[186:189], v[88:91]
	v_mfma_f32_16x16x32_bf16 v[84:87], v[154:157], v[186:189], v[84:87]
	v_mfma_f32_16x16x32_bf16 v[84:87], v[158:161], v[190:193], v[84:87]
	v_mfma_f32_16x16x32_bf16 v[100:103], v[158:161], v[182:185], v[100:103]
	v_mfma_f32_16x16x32_bf16 v[100:103], v[154:157], v[178:181], v[100:103]
	v_mfma_f32_16x16x32_bf16 v[116:119], v[154:157], v[170:173], v[116:119]
	v_mfma_f32_16x16x32_bf16 v[116:119], v[158:161], v[174:177], v[116:119]
	v_mfma_f32_16x16x32_bf16 v[124:127], v[158:161], v[166:169], v[124:127]
	s_setprio 0
	v_mfma_f32_16x16x32_bf16 v[124:127], v[154:157], v[162:165], v[124:127]
	s_barrier
	s_add_i32 s18, 0, 0x1c000
	s_add_i32 s19, s42, s26
	v_add_u32_e32 v145, s18, v142
	v_lshl_add_u64 v[212:213], v[212:213], 0, s[2:3]
	s_mov_b32 m0, s19
	ds_read_b128 v[194:197], v145
	ds_read_b128 v[200:203], v145 offset:1024
	ds_read_b128 v[204:207], v145 offset:2048
	ds_read_b128 v[208:211], v145 offset:3072
	global_load_lds_dwordx4 v[212:213], off
	v_lshl_add_u64 v[212:213], v[214:215], 0, s[2:3]
	s_add_i32 m0, s19, 0x2000
	s_nop 0
	global_load_lds_dwordx4 v[212:213], off
	s_setprio 1
	s_barrier
	s_waitcnt lgkmcnt(0)
	v_mfma_f32_16x16x32_bf16 v[112:115], v[194:197], v[162:165], v[112:115]
	v_mfma_f32_16x16x32_bf16 v[112:115], v[200:203], v[166:169], v[112:115]
	v_mfma_f32_16x16x32_bf16 v[96:99], v[200:203], v[174:177], v[96:99]
	v_mfma_f32_16x16x32_bf16 v[96:99], v[194:197], v[170:173], v[96:99]
	v_mfma_f32_16x16x32_bf16 v[80:83], v[194:197], v[178:181], v[80:83]
	v_mfma_f32_16x16x32_bf16 v[80:83], v[200:203], v[182:185], v[80:83]
	v_mfma_f32_16x16x32_bf16 v[72:75], v[200:203], v[190:193], v[72:75]
	v_mfma_f32_16x16x32_bf16 v[72:75], v[194:197], v[186:189], v[72:75]
	v_mfma_f32_16x16x32_bf16 v[68:71], v[204:207], v[186:189], v[68:71]
	v_mfma_f32_16x16x32_bf16 v[68:71], v[208:211], v[190:193], v[68:71]
	v_mfma_f32_16x16x32_bf16 v[76:79], v[208:211], v[182:185], v[76:79]
	v_mfma_f32_16x16x32_bf16 v[76:79], v[204:207], v[178:181], v[76:79]
	v_mfma_f32_16x16x32_bf16 v[92:95], v[204:207], v[170:173], v[92:95]
	v_mfma_f32_16x16x32_bf16 v[92:95], v[208:211], v[174:177], v[92:95]
	v_mfma_f32_16x16x32_bf16 v[108:111], v[208:211], v[166:169], v[108:111]
	s_setprio 0
	v_mfma_f32_16x16x32_bf16 v[108:111], v[204:207], v[162:165], v[108:111]
	s_barrier
	s_mov_b32 m0, s31
	v_lshl_add_u64 v[212:213], v[216:217], 0, s[2:3]
	ds_read_b128 v[162:165], v144 offset:49152
	ds_read_b128 v[166:169], v144 offset:50176
	ds_read_b128 v[170:173], v144 offset:51200
	ds_read_b128 v[174:177], v144 offset:52224
	ds_read_b128 v[178:181], v144 offset:53248
	ds_read_b128 v[182:185], v144 offset:54272
	ds_read_b128 v[186:189], v144 offset:55296
	ds_read_b128 v[190:193], v144 offset:56320
	global_load_lds_dwordx4 v[212:213], off
	v_lshl_add_u64 v[212:213], v[218:219], 0, s[2:3]
	s_mov_b32 m0, s33
	s_nop 0
	global_load_lds_dwordx4 v[212:213], off
	s_waitcnt vmcnt(10)
	s_setprio 1
	s_barrier
	s_waitcnt lgkmcnt(0)
	v_mfma_f32_16x16x32_bf16 v[64:67], v[146:149], v[162:165], v[64:67]
	v_mfma_f32_16x16x32_bf16 v[64:67], v[150:153], v[166:169], v[64:67]
	v_mfma_f32_16x16x32_bf16 v[56:59], v[150:153], v[174:177], v[56:59]
	v_mfma_f32_16x16x32_bf16 v[56:59], v[146:149], v[170:173], v[56:59]
	v_mfma_f32_16x16x32_bf16 v[40:43], v[146:149], v[178:181], v[40:43]
	v_mfma_f32_16x16x32_bf16 v[40:43], v[150:153], v[182:185], v[40:43]
	v_mfma_f32_16x16x32_bf16 v[24:27], v[150:153], v[190:193], v[24:27]
	v_mfma_f32_16x16x32_bf16 v[24:27], v[146:149], v[186:189], v[24:27]
	v_mfma_f32_16x16x32_bf16 v[20:23], v[154:157], v[186:189], v[20:23]
	v_mfma_f32_16x16x32_bf16 v[20:23], v[158:161], v[190:193], v[20:23]
	v_mfma_f32_16x16x32_bf16 v[36:39], v[158:161], v[182:185], v[36:39]
	v_mfma_f32_16x16x32_bf16 v[36:39], v[154:157], v[178:181], v[36:39]
	v_mfma_f32_16x16x32_bf16 v[52:55], v[154:157], v[170:173], v[52:55]
	v_mfma_f32_16x16x32_bf16 v[52:55], v[158:161], v[174:177], v[52:55]
	v_mfma_f32_16x16x32_bf16 v[60:63], v[158:161], v[166:169], v[60:63]
	s_setprio 0
	v_mfma_f32_16x16x32_bf16 v[60:63], v[154:157], v[162:165], v[60:63]
	s_barrier
	s_add_u32 s16, s16, 0x20080
	s_addc_u32 s17, s17, 0
	s_add_i32 s18, s18, s26
	s_mov_b32 m0, s18
	s_nop 0
	global_load_lds_dwordx4 v2, s[16:17]
	s_add_i32 m0, s18, 0x2000
	s_nop 0
	global_load_lds_dwordx4 v132, s[16:17]
	v_add_u32_e32 v145, 0x10000, v142
	ds_read_b128 v[146:149], v145
	ds_read_b128 v[150:153], v145 offset:1024
	ds_read_b128 v[154:157], v145 offset:2048
	ds_read_b128 v[158:161], v145 offset:3072
	s_waitcnt vmcnt(6)
	s_setprio 1
	s_barrier
	v_mfma_f32_16x16x32_bf16 v[48:51], v[194:197], v[162:165], v[48:51]
	v_mfma_f32_16x16x32_bf16 v[48:51], v[200:203], v[166:169], v[48:51]
	v_mfma_f32_16x16x32_bf16 v[32:35], v[200:203], v[174:177], v[32:35]
	v_mfma_f32_16x16x32_bf16 v[32:35], v[194:197], v[170:173], v[32:35]
	v_mfma_f32_16x16x32_bf16 v[16:19], v[194:197], v[178:181], v[16:19]
	v_mfma_f32_16x16x32_bf16 v[16:19], v[200:203], v[182:185], v[16:19]
	v_mfma_f32_16x16x32_bf16 v[8:11], v[200:203], v[190:193], v[8:11]
	v_mfma_f32_16x16x32_bf16 v[8:11], v[194:197], v[186:189], v[8:11]
	v_mfma_f32_16x16x32_bf16 v[4:7], v[204:207], v[186:189], v[4:7]
	v_mfma_f32_16x16x32_bf16 v[4:7], v[208:211], v[190:193], v[4:7]
	v_mfma_f32_16x16x32_bf16 v[12:15], v[208:211], v[182:185], v[12:15]
	v_mfma_f32_16x16x32_bf16 v[12:15], v[204:207], v[178:181], v[12:15]
	v_mfma_f32_16x16x32_bf16 v[28:31], v[204:207], v[170:173], v[28:31]
	v_mfma_f32_16x16x32_bf16 v[28:31], v[208:211], v[174:177], v[28:31]
	v_mfma_f32_16x16x32_bf16 v[44:47], v[208:211], v[166:169], v[44:47]
	s_setprio 0
	v_mfma_f32_16x16x32_bf16 v[44:47], v[204:207], v[162:165], v[44:47]
	s_barrier
	s_add_i32 s41, s41, 2
	s_add_u32 s14, s14, 0x100
	s_addc_u32 s15, s15, 0
	s_add_u32 s39, s39, 0x100
	s_addc_u32 s40, s40, 0
	s_cmp_gt_u32 s41, 29
	s_cbranch_scc0 .LBB0_95
	v_lshl_add_u32 v145, s36, 8, v1
	v_lshl_or_b32 v202, s35, 8, v143
	v_ashrrev_i32_e32 v203, 31, v202
	v_mov_b64_e32 v[204:205], s[4:5]
	s_mov_b32 s7, 0x8200
	v_cvt_pk_bf16_f32 v72, v72, v73
	v_cvt_pk_bf16_f32 v73, v74, v75
	v_cvt_pk_bf16_f32 v74, v68, v69
	v_add_u32_e32 v68, 0x80, v145
	v_mad_i64_i32 v[206:207], s[14:15], v145, s7, v[204:205]
	v_lshlrev_b64 v[202:203], 1, v[202:203]
	v_cvt_pk_bf16_f32 v112, v112, v113
	v_cvt_pk_bf16_f32 v113, v114, v115
	v_cvt_pk_bf16_f32 v114, v108, v109
	v_or_b32_e32 v108, 16, v145
	v_mad_i64_i32 v[68:69], s[14:15], v68, s7, v[204:205]
	v_cvt_pk_bf16_f32 v48, v48, v49
	v_cvt_pk_bf16_f32 v49, v50, v51
	v_cvt_pk_bf16_f32 v50, v44, v45
	v_add_u32_e32 v44, 0x90, v145
	v_lshl_add_u64 v[206:207], v[206:207], 0, v[202:203]
	v_cvt_pk_bf16_f32 v115, v110, v111
	v_mad_i64_i32 v[108:109], s[14:15], v108, s7, v[204:205]
	v_cvt_pk_bf16_f32 v96, v96, v97
	v_cvt_pk_bf16_f32 v97, v98, v99
	v_cvt_pk_bf16_f32 v98, v92, v93
	v_or_b32_e32 v92, 32, v145
	v_lshl_add_u64 v[68:69], v[68:69], 0, v[202:203]
	v_cvt_pk_bf16_f32 v51, v46, v47
	v_mad_i64_i32 v[44:45], s[14:15], v44, s7, v[204:205]
	v_cvt_pk_bf16_f32 v32, v32, v33
	v_cvt_pk_bf16_f32 v33, v34, v35
	v_cvt_pk_bf16_f32 v34, v28, v29
	v_add_u32_e32 v28, 0xa0, v145
	global_store_dwordx4 v[206:207], v[112:115], off offset:64 nt
	v_cvt_pk_bf16_f32 v99, v94, v95
	v_mad_i64_i32 v[92:93], s[14:15], v92, s7, v[204:205]
	v_lshl_add_u64 v[112:113], v[108:109], 0, v[202:203]
	v_cvt_pk_bf16_f32 v80, v80, v81
	v_cvt_pk_bf16_f32 v81, v82, v83
	v_cvt_pk_bf16_f32 v82, v76, v77
	v_or_b32_e32 v76, 48, v145
	global_store_dwordx4 v[68:69], v[48:51], off offset:64 nt
	v_cvt_pk_bf16_f32 v35, v30, v31
	v_mad_i64_i32 v[28:29], s[14:15], v28, s7, v[204:205]
	v_lshl_add_u64 v[48:49], v[44:45], 0, v[202:203]
	v_cvt_pk_bf16_f32 v16, v16, v17
	v_cvt_pk_bf16_f32 v17, v18, v19
	v_cvt_pk_bf16_f32 v18, v12, v13
	v_add_u32_e32 v12, 0xb0, v145
	global_store_dwordx4 v[112:113], v[96:99], off offset:64 nt
	v_cvt_pk_bf16_f32 v83, v78, v79
	v_mad_i64_i32 v[76:77], s[14:15], v76, s7, v[204:205]
	v_lshl_add_u64 v[96:97], v[92:93], 0, v[202:203]
	global_store_dwordx4 v[48:49], v[32:35], off offset:64 nt
	v_cvt_pk_bf16_f32 v19, v14, v15
	v_mad_i64_i32 v[12:13], s[14:15], v12, s7, v[204:205]
	v_lshl_add_u64 v[32:33], v[28:29], 0, v[202:203]
	v_cvt_pk_bf16_f32 v128, v128, v129
	v_cvt_pk_bf16_f32 v129, v130, v131
	v_cvt_pk_bf16_f32 v130, v124, v125
	v_cvt_pk_bf16_f32 v131, v126, v127
	v_cvt_pk_bf16_f32 v108, v120, v121
	v_cvt_pk_bf16_f32 v109, v122, v123
	v_cvt_pk_bf16_f32 v110, v116, v117
	v_cvt_pk_bf16_f32 v111, v118, v119
	v_cvt_pk_bf16_f32 v92, v104, v105
	v_cvt_pk_bf16_f32 v93, v106, v107
	v_cvt_pk_bf16_f32 v94, v100, v101
	v_cvt_pk_bf16_f32 v95, v102, v103
	global_store_dwordx4 v[96:97], v[80:83], off offset:64 nt
	v_cvt_pk_bf16_f32 v78, v84, v85
	v_cvt_pk_bf16_f32 v79, v86, v87
	v_lshl_add_u64 v[80:81], v[76:77], 0, v[202:203]
	v_cvt_pk_bf16_f32 v76, v88, v89
	v_cvt_pk_bf16_f32 v77, v90, v91
	v_cvt_pk_bf16_f32 v75, v70, v71
	v_cvt_pk_bf16_f32 v64, v64, v65
	v_cvt_pk_bf16_f32 v65, v66, v67
	v_cvt_pk_bf16_f32 v66, v60, v61
	v_cvt_pk_bf16_f32 v67, v62, v63
	v_cvt_pk_bf16_f32 v44, v56, v57
	v_cvt_pk_bf16_f32 v45, v58, v59
	v_cvt_pk_bf16_f32 v46, v52, v53
	v_cvt_pk_bf16_f32 v47, v54, v55
	v_cvt_pk_bf16_f32 v28, v40, v41
	v_cvt_pk_bf16_f32 v29, v42, v43
	v_cvt_pk_bf16_f32 v30, v36, v37
	v_cvt_pk_bf16_f32 v31, v38, v39
	global_store_dwordx4 v[32:33], v[16:19], off offset:64 nt
	v_cvt_pk_bf16_f32 v14, v20, v21
	v_cvt_pk_bf16_f32 v15, v22, v23
	v_lshl_add_u64 v[16:17], v[12:13], 0, v[202:203]
	v_cvt_pk_bf16_f32 v12, v24, v25
	v_cvt_pk_bf16_f32 v13, v26, v27
	v_cvt_pk_bf16_f32 v8, v8, v9
	v_cvt_pk_bf16_f32 v9, v10, v11
	v_cvt_pk_bf16_f32 v10, v4, v5
	v_cvt_pk_bf16_f32 v11, v6, v7
	s_and_b64 vcc, exec, s[0:1]
	s_mov_b32 s35, s6
	s_mov_b32 s36, s8
	s_mov_b64 s[16:17], s[12:13]
	s_mov_b64 s[14:15], s[10:11]
	global_store_dwordx4 v[206:207], v[128:131], off nt
	global_store_dwordx4 v[112:113], v[108:111], off nt
	global_store_dwordx4 v[96:97], v[92:95], off nt
	global_store_dwordx4 v[80:81], v[76:79], off nt
	global_store_dwordx4 v[80:81], v[72:75], off offset:64 nt
	global_store_dwordx4 v[68:69], v[64:67], off nt
	global_store_dwordx4 v[48:49], v[44:47], off nt
	global_store_dwordx4 v[32:33], v[28:31], off nt
	global_store_dwordx4 v[16:17], v[12:15], off nt
	global_store_dwordx4 v[16:17], v[8:11], off offset:64 nt
	s_cbranch_vccz .LBB0_92
	s_waitcnt lgkmcnt(0)
	s_waitcnt vmcnt(0)
	s_cmpk_gt_u32 s21, 0xff
	s_cbranch_scc1 .LBB0_99
	s_barrier

.LBB0_236:
	s_add_u32 s16, s14, 0xfffe0080
	s_addc_u32 s17, s15, -1
	s_add_i32 s41, 0, 0x10000
	v_add_u32_e32 v145, s41, v142
	ds_read_b128 v[146:149], v145
	ds_read_b128 v[150:153], v145 offset:1024
	ds_read_b128 v[154:157], v145 offset:2048
	ds_read_b128 v[158:161], v145 offset:3072
	s_cmp_eq_u32 s40, 4
	s_cselect_b32 s19, s9, s17
	s_cselect_b32 s18, s36, s16
	s_cselect_b32 s17, s7, s39
	s_cselect_b32 s16, s37, s38
	s_add_i32 m0, s26, 0xc000
	ds_read_b128 v[162:165], v144
	ds_read_b128 v[166:169], v144 offset:1024
	ds_read_b128 v[170:173], v144 offset:2048
	ds_read_b128 v[174:177], v144 offset:3072
	ds_read_b128 v[178:181], v144 offset:4096
	ds_read_b128 v[182:185], v144 offset:5120
	ds_read_b128 v[186:189], v144 offset:6144
	ds_read_b128 v[190:193], v144 offset:7168
	global_load_lds_dwordx4 v138, s[14:15]
	s_add_i32 m0, s26, 0xe000
	s_nop 0
	global_load_lds_dwordx4 v140, s[14:15]
	s_waitcnt lgkmcnt(8)
	s_setprio 1
	s_barrier
	s_waitcnt lgkmcnt(0)
	v_mfma_f32_16x16x32_bf16 v[128:131], v[146:149], v[162:165], v[128:131]
	v_mfma_f32_16x16x32_bf16 v[128:131], v[150:153], v[166:169], v[128:131]
	v_mfma_f32_16x16x32_bf16 v[120:123], v[150:153], v[174:177], v[120:123]
	v_mfma_f32_16x16x32_bf16 v[120:123], v[146:149], v[170:173], v[120:123]
	v_mfma_f32_16x16x32_bf16 v[104:107], v[146:149], v[178:181], v[104:107]
	v_mfma_f32_16x16x32_bf16 v[104:107], v[150:153], v[182:185], v[104:107]
	v_mfma_f32_16x16x32_bf16 v[88:91], v[150:153], v[190:193], v[88:91]
	v_mfma_f32_16x16x32_bf16 v[88:91], v[146:149], v[186:189], v[88:91]
	v_mfma_f32_16x16x32_bf16 v[84:87], v[154:157], v[186:189], v[84:87]
	v_mfma_f32_16x16x32_bf16 v[84:87], v[158:161], v[190:193], v[84:87]
	v_mfma_f32_16x16x32_bf16 v[100:103], v[158:161], v[182:185], v[100:103]
	v_mfma_f32_16x16x32_bf16 v[100:103], v[154:157], v[178:181], v[100:103]
	v_mfma_f32_16x16x32_bf16 v[116:119], v[154:157], v[170:173], v[116:119]
	v_mfma_f32_16x16x32_bf16 v[116:119], v[158:161], v[174:177], v[116:119]
	v_mfma_f32_16x16x32_bf16 v[124:127], v[158:161], v[166:169], v[124:127]
	s_setprio 0
	v_mfma_f32_16x16x32_bf16 v[124:127], v[154:157], v[162:165], v[124:127]
	s_barrier
	s_add_i32 s44, 0, 0x14000
	s_add_i32 s41, s41, s25
	v_add_u32_e32 v145, s44, v142
	v_lshl_add_u64 v[212:213], s[16:17], 0, v[2:3]
	s_mov_b32 m0, s41
	ds_read_b128 v[194:197], v145
	ds_read_b128 v[200:203], v145 offset:1024
	ds_read_b128 v[204:207], v145 offset:2048
	ds_read_b128 v[208:211], v145 offset:3072
	global_load_lds_dwordx4 v[212:213], off
	v_lshl_add_u64 v[214:215], s[16:17], 0, v[132:133]
	s_add_i32 m0, s41, 0x2000
	s_nop 0
	global_load_lds_dwordx4 v[214:215], off
	s_setprio 1
	s_barrier
	s_waitcnt lgkmcnt(0)
	v_mfma_f32_16x16x32_bf16 v[112:115], v[194:197], v[162:165], v[112:115]
	v_mfma_f32_16x16x32_bf16 v[112:115], v[200:203], v[166:169], v[112:115]
	v_mfma_f32_16x16x32_bf16 v[96:99], v[200:203], v[174:177], v[96:99]
	v_mfma_f32_16x16x32_bf16 v[96:99], v[194:197], v[170:173], v[96:99]
	v_mfma_f32_16x16x32_bf16 v[80:83], v[194:197], v[178:181], v[80:83]
	v_mfma_f32_16x16x32_bf16 v[80:83], v[200:203], v[182:185], v[80:83]
	v_mfma_f32_16x16x32_bf16 v[72:75], v[200:203], v[190:193], v[72:75]
	v_mfma_f32_16x16x32_bf16 v[72:75], v[194:197], v[186:189], v[72:75]
	v_mfma_f32_16x16x32_bf16 v[68:71], v[204:207], v[186:189], v[68:71]
	v_mfma_f32_16x16x32_bf16 v[68:71], v[208:211], v[190:193], v[68:71]
	v_mfma_f32_16x16x32_bf16 v[76:79], v[208:211], v[182:185], v[76:79]
	v_mfma_f32_16x16x32_bf16 v[76:79], v[204:207], v[178:181], v[76:79]
	v_mfma_f32_16x16x32_bf16 v[92:95], v[204:207], v[170:173], v[92:95]
	v_mfma_f32_16x16x32_bf16 v[92:95], v[208:211], v[174:177], v[92:95]
	v_mfma_f32_16x16x32_bf16 v[108:111], v[208:211], v[166:169], v[108:111]
	s_setprio 0
	v_mfma_f32_16x16x32_bf16 v[108:111], v[204:207], v[162:165], v[108:111]
	s_barrier
	s_mov_b32 m0, s26
	v_lshl_add_u64 v[216:217], s[18:19], 0, v[136:137]
	ds_read_b128 v[162:165], v144 offset:16384
	ds_read_b128 v[166:169], v144 offset:17408
	ds_read_b128 v[170:173], v144 offset:18432
	ds_read_b128 v[174:177], v144 offset:19456
	ds_read_b128 v[178:181], v144 offset:20480
	ds_read_b128 v[182:185], v144 offset:21504
	ds_read_b128 v[186:189], v144 offset:22528
	ds_read_b128 v[190:193], v144 offset:23552
	global_load_lds_dwordx4 v[216:217], off
	v_lshl_add_u64 v[218:219], s[18:19], 0, v[134:135]
	s_mov_b32 m0, s27
	s_nop 0
	global_load_lds_dwordx4 v[218:219], off
	s_waitcnt vmcnt(10)
	s_setprio 1
	s_barrier
	s_waitcnt lgkmcnt(0)
	v_mfma_f32_16x16x32_bf16 v[64:67], v[146:149], v[162:165], v[64:67]
	v_mfma_f32_16x16x32_bf16 v[64:67], v[150:153], v[166:169], v[64:67]
	v_mfma_f32_16x16x32_bf16 v[56:59], v[150:153], v[174:177], v[56:59]
	v_mfma_f32_16x16x32_bf16 v[56:59], v[146:149], v[170:173], v[56:59]
	v_mfma_f32_16x16x32_bf16 v[40:43], v[146:149], v[178:181], v[40:43]
	v_mfma_f32_16x16x32_bf16 v[40:43], v[150:153], v[182:185], v[40:43]
	v_mfma_f32_16x16x32_bf16 v[24:27], v[150:153], v[190:193], v[24:27]
	v_mfma_f32_16x16x32_bf16 v[24:27], v[146:149], v[186:189], v[24:27]
	v_mfma_f32_16x16x32_bf16 v[20:23], v[154:157], v[186:189], v[20:23]
	v_mfma_f32_16x16x32_bf16 v[20:23], v[158:161], v[190:193], v[20:23]
	v_mfma_f32_16x16x32_bf16 v[36:39], v[158:161], v[182:185], v[36:39]
	v_mfma_f32_16x16x32_bf16 v[36:39], v[154:157], v[178:181], v[36:39]
	v_mfma_f32_16x16x32_bf16 v[52:55], v[154:157], v[170:173], v[52:55]
	v_mfma_f32_16x16x32_bf16 v[52:55], v[158:161], v[174:177], v[52:55]
	v_mfma_f32_16x16x32_bf16 v[60:63], v[158:161], v[166:169], v[60:63]
	s_setprio 0
	v_mfma_f32_16x16x32_bf16 v[60:63], v[154:157], v[162:165], v[60:63]
	s_barrier
	s_add_u32 s42, s16, 0x8000
	s_addc_u32 s43, s17, 0
	s_add_i32 s41, s44, s25
	s_mov_b32 m0, s41
	s_nop 0
	global_load_lds_dwordx4 v2, s[42:43]
	s_add_i32 m0, s41, 0x2000
	s_nop 0
	global_load_lds_dwordx4 v132, s[42:43]
	s_add_i32 s41, 0, 0x18000
	v_add_u32_e32 v145, s41, v142
	ds_read_b128 v[146:149], v145
	ds_read_b128 v[150:153], v145 offset:1024
	ds_read_b128 v[154:157], v145 offset:2048
	ds_read_b128 v[158:161], v145 offset:3072
	s_waitcnt vmcnt(6)
	s_setprio 1
	s_barrier
	v_mfma_f32_16x16x32_bf16 v[48:51], v[194:197], v[162:165], v[48:51]
	v_mfma_f32_16x16x32_bf16 v[48:51], v[200:203], v[166:169], v[48:51]
	v_mfma_f32_16x16x32_bf16 v[32:35], v[200:203], v[174:177], v[32:35]
	v_mfma_f32_16x16x32_bf16 v[32:35], v[194:197], v[170:173], v[32:35]
	v_mfma_f32_16x16x32_bf16 v[16:19], v[194:197], v[178:181], v[16:19]
	v_mfma_f32_16x16x32_bf16 v[16:19], v[200:203], v[182:185], v[16:19]
	v_mfma_f32_16x16x32_bf16 v[8:11], v[200:203], v[190:193], v[8:11]
	v_mfma_f32_16x16x32_bf16 v[8:11], v[194:197], v[186:189], v[8:11]
	v_mfma_f32_16x16x32_bf16 v[4:7], v[204:207], v[186:189], v[4:7]
	v_mfma_f32_16x16x32_bf16 v[4:7], v[208:211], v[190:193], v[4:7]
	v_mfma_f32_16x16x32_bf16 v[12:15], v[208:211], v[182:185], v[12:15]
	v_mfma_f32_16x16x32_bf16 v[12:15], v[204:207], v[178:181], v[12:15]
	v_mfma_f32_16x16x32_bf16 v[28:31], v[204:207], v[170:173], v[28:31]
	v_mfma_f32_16x16x32_bf16 v[28:31], v[208:211], v[174:177], v[28:31]
	v_mfma_f32_16x16x32_bf16 v[44:47], v[208:211], v[166:169], v[44:47]
	s_setprio 0
	v_mfma_f32_16x16x32_bf16 v[44:47], v[204:207], v[162:165], v[44:47]
	s_barrier
	s_add_u32 s18, s18, 0x20000
	s_addc_u32 s19, s19, 0
	s_mov_b32 m0, s28
	ds_read_b128 v[162:165], v144 offset:32768
	ds_read_b128 v[166:169], v144 offset:33792
	ds_read_b128 v[170:173], v144 offset:34816
	ds_read_b128 v[174:177], v144 offset:35840
	ds_read_b128 v[178:181], v144 offset:36864
	ds_read_b128 v[182:185], v144 offset:37888
	ds_read_b128 v[186:189], v144 offset:38912
	ds_read_b128 v[190:193], v144 offset:39936
	global_load_lds_dwordx4 v136, s[18:19]
	s_mov_b32 m0, s29
	s_nop 0
	global_load_lds_dwordx4 v134, s[18:19]
	s_waitcnt lgkmcnt(8)
	s_setprio 1
	s_barrier
	s_waitcnt lgkmcnt(0)
	v_mfma_f32_16x16x32_bf16 v[128:131], v[146:149], v[162:165], v[128:131]
	v_mfma_f32_16x16x32_bf16 v[128:131], v[150:153], v[166:169], v[128:131]
	v_mfma_f32_16x16x32_bf16 v[120:123], v[150:153], v[174:177], v[120:123]
	v_mfma_f32_16x16x32_bf16 v[120:123], v[146:149], v[170:173], v[120:123]
	v_mfma_f32_16x16x32_bf16 v[104:107], v[146:149], v[178:181], v[104:107]
	v_mfma_f32_16x16x32_bf16 v[104:107], v[150:153], v[182:185], v[104:107]
	v_mfma_f32_16x16x32_bf16 v[88:91], v[150:153], v[190:193], v[88:91]
	v_mfma_f32_16x16x32_bf16 v[88:91], v[146:149], v[186:189], v[88:91]
	v_mfma_f32_16x16x32_bf16 v[84:87], v[154:157], v[186:189], v[84:87]
	v_mfma_f32_16x16x32_bf16 v[84:87], v[158:161], v[190:193], v[84:87]
	v_mfma_f32_16x16x32_bf16 v[100:103], v[158:161], v[182:185], v[100:103]
	v_mfma_f32_16x16x32_bf16 v[100:103], v[154:157], v[178:181], v[100:103]
	v_mfma_f32_16x16x32_bf16 v[116:119], v[154:157], v[170:173], v[116:119]
	v_mfma_f32_16x16x32_bf16 v[116:119], v[158:161], v[174:177], v[116:119]
	v_mfma_f32_16x16x32_bf16 v[124:127], v[158:161], v[166:169], v[124:127]
	s_setprio 0
	v_mfma_f32_16x16x32_bf16 v[124:127], v[154:157], v[162:165], v[124:127]
	s_barrier
	s_add_i32 s18, 0, 0x1c000
	s_add_i32 s19, s41, s25
	v_add_u32_e32 v145, s18, v142
	v_lshl_add_u64 v[212:213], v[212:213], 0, s[2:3]
	s_mov_b32 m0, s19
	ds_read_b128 v[194:197], v145
	ds_read_b128 v[200:203], v145 offset:1024
	ds_read_b128 v[204:207], v145 offset:2048
	ds_read_b128 v[208:211], v145 offset:3072
	global_load_lds_dwordx4 v[212:213], off
	v_lshl_add_u64 v[212:213], v[214:215], 0, s[2:3]
	s_add_i32 m0, s19, 0x2000
	s_nop 0
	global_load_lds_dwordx4 v[212:213], off
	s_setprio 1
	s_barrier
	s_waitcnt lgkmcnt(0)
	v_mfma_f32_16x16x32_bf16 v[112:115], v[194:197], v[162:165], v[112:115]
	v_mfma_f32_16x16x32_bf16 v[112:115], v[200:203], v[166:169], v[112:115]
	v_mfma_f32_16x16x32_bf16 v[96:99], v[200:203], v[174:177], v[96:99]
	v_mfma_f32_16x16x32_bf16 v[96:99], v[194:197], v[170:173], v[96:99]
	v_mfma_f32_16x16x32_bf16 v[80:83], v[194:197], v[178:181], v[80:83]
	v_mfma_f32_16x16x32_bf16 v[80:83], v[200:203], v[182:185], v[80:83]
	v_mfma_f32_16x16x32_bf16 v[72:75], v[200:203], v[190:193], v[72:75]
	v_mfma_f32_16x16x32_bf16 v[72:75], v[194:197], v[186:189], v[72:75]
	v_mfma_f32_16x16x32_bf16 v[68:71], v[204:207], v[186:189], v[68:71]
	v_mfma_f32_16x16x32_bf16 v[68:71], v[208:211], v[190:193], v[68:71]
	v_mfma_f32_16x16x32_bf16 v[76:79], v[208:211], v[182:185], v[76:79]
	v_mfma_f32_16x16x32_bf16 v[76:79], v[204:207], v[178:181], v[76:79]
	v_mfma_f32_16x16x32_bf16 v[92:95], v[204:207], v[170:173], v[92:95]
	v_mfma_f32_16x16x32_bf16 v[92:95], v[208:211], v[174:177], v[92:95]
	v_mfma_f32_16x16x32_bf16 v[108:111], v[208:211], v[166:169], v[108:111]
	s_setprio 0
	v_mfma_f32_16x16x32_bf16 v[108:111], v[204:207], v[162:165], v[108:111]
	s_barrier
	s_mov_b32 m0, s30
	v_lshl_add_u64 v[212:213], v[216:217], 0, s[2:3]
	ds_read_b128 v[162:165], v144 offset:49152
	ds_read_b128 v[166:169], v144 offset:50176
	ds_read_b128 v[170:173], v144 offset:51200
	ds_read_b128 v[174:177], v144 offset:52224
	ds_read_b128 v[178:181], v144 offset:53248
	ds_read_b128 v[182:185], v144 offset:54272
	ds_read_b128 v[186:189], v144 offset:55296
	ds_read_b128 v[190:193], v144 offset:56320
	global_load_lds_dwordx4 v[212:213], off
	v_lshl_add_u64 v[212:213], v[218:219], 0, s[2:3]
	s_mov_b32 m0, s31
	s_nop 0
	global_load_lds_dwordx4 v[212:213], off
	s_setprio 1
	s_barrier
	s_waitcnt lgkmcnt(0)
	v_mfma_f32_16x16x32_bf16 v[64:67], v[146:149], v[162:165], v[64:67]
	v_mfma_f32_16x16x32_bf16 v[64:67], v[150:153], v[166:169], v[64:67]
	v_mfma_f32_16x16x32_bf16 v[56:59], v[150:153], v[174:177], v[56:59]
	v_mfma_f32_16x16x32_bf16 v[56:59], v[146:149], v[170:173], v[56:59]
	v_mfma_f32_16x16x32_bf16 v[40:43], v[146:149], v[178:181], v[40:43]
	v_mfma_f32_16x16x32_bf16 v[40:43], v[150:153], v[182:185], v[40:43]
	v_mfma_f32_16x16x32_bf16 v[24:27], v[150:153], v[190:193], v[24:27]
	v_mfma_f32_16x16x32_bf16 v[24:27], v[146:149], v[186:189], v[24:27]
	v_mfma_f32_16x16x32_bf16 v[20:23], v[154:157], v[186:189], v[20:23]
	v_mfma_f32_16x16x32_bf16 v[20:23], v[158:161], v[190:193], v[20:23]
	v_mfma_f32_16x16x32_bf16 v[36:39], v[158:161], v[182:185], v[36:39]
	v_mfma_f32_16x16x32_bf16 v[36:39], v[154:157], v[178:181], v[36:39]
	v_mfma_f32_16x16x32_bf16 v[52:55], v[154:157], v[170:173], v[52:55]
	v_mfma_f32_16x16x32_bf16 v[52:55], v[158:161], v[174:177], v[52:55]
	v_mfma_f32_16x16x32_bf16 v[60:63], v[158:161], v[166:169], v[60:63]
	s_setprio 0
	v_mfma_f32_16x16x32_bf16 v[60:63], v[154:157], v[162:165], v[60:63]
	s_barrier
	s_add_u32 s16, s16, 0x8080
	s_addc_u32 s17, s17, 0
	s_add_i32 s18, s18, s25
	s_mov_b32 m0, s18
	s_nop 0
	global_load_lds_dwordx4 v2, s[16:17]
	s_add_i32 m0, s18, 0x2000
	s_nop 0
	global_load_lds_dwordx4 v132, s[16:17]
	s_waitcnt vmcnt(6)
	s_setprio 1
	s_barrier
	v_mfma_f32_16x16x32_bf16 v[48:51], v[194:197], v[162:165], v[48:51]
	v_mfma_f32_16x16x32_bf16 v[48:51], v[200:203], v[166:169], v[48:51]
	v_mfma_f32_16x16x32_bf16 v[32:35], v[200:203], v[174:177], v[32:35]
	v_mfma_f32_16x16x32_bf16 v[32:35], v[194:197], v[170:173], v[32:35]
	v_mfma_f32_16x16x32_bf16 v[16:19], v[194:197], v[178:181], v[16:19]
	v_mfma_f32_16x16x32_bf16 v[16:19], v[200:203], v[182:185], v[16:19]
	v_mfma_f32_16x16x32_bf16 v[8:11], v[200:203], v[190:193], v[8:11]
	v_mfma_f32_16x16x32_bf16 v[8:11], v[194:197], v[186:189], v[8:11]
	v_mfma_f32_16x16x32_bf16 v[4:7], v[204:207], v[186:189], v[4:7]
	v_mfma_f32_16x16x32_bf16 v[4:7], v[208:211], v[190:193], v[4:7]
	v_mfma_f32_16x16x32_bf16 v[12:15], v[208:211], v[182:185], v[12:15]
	v_mfma_f32_16x16x32_bf16 v[12:15], v[204:207], v[178:181], v[12:15]
	v_mfma_f32_16x16x32_bf16 v[28:31], v[204:207], v[170:173], v[28:31]
	v_mfma_f32_16x16x32_bf16 v[28:31], v[208:211], v[174:177], v[28:31]
	v_mfma_f32_16x16x32_bf16 v[44:47], v[208:211], v[166:169], v[44:47]
	s_setprio 0
	v_mfma_f32_16x16x32_bf16 v[44:47], v[204:207], v[162:165], v[44:47]
	s_barrier
	s_add_i32 s40, s40, 2
	s_add_u32 s14, s14, 0x100
	s_addc_u32 s15, s15, 0
	s_add_u32 s38, s38, 0x100
	s_addc_u32 s39, s39, 0
	s_cmp_gt_u32 s40, 5
	s_cbranch_scc0 .LBB0_236
	v_lshl_add_u32 v146, s35, 8, v1
	v_lshl_or_b32 v148, s34, 8, v143
	v_ashrrev_i32_e32 v147, 31, v146
	v_ashrrev_i32_e32 v149, 31, v148
	v_lshlrev_b64 v[150:151], 12, v[146:147]
	v_lshl_add_u64 v[150:151], s[4:5], 0, v[150:151]
	v_lshlrev_b64 v[148:149], 1, v[148:149]
	v_lshl_add_u64 v[150:151], v[150:151], 0, v[148:149]
	s_mov_b32 s7, 0x80000
	s_mov_b64 s[14:15], 0x80000
	v_cvt_pk_bf16_f32 v64, v64, v65
	v_cvt_pk_bf16_f32 v65, v66, v67
	v_cvt_pk_bf16_f32 v66, v60, v61
	v_add_co_u32_e32 v60, vcc, s7, v150
	v_cvt_pk_bf16_f32 v72, v72, v73
	v_cvt_pk_bf16_f32 v73, v74, v75
	v_cvt_pk_bf16_f32 v74, v68, v69
	v_lshl_add_u64 v[68:69], v[150:151], 0, s[14:15]
	v_addc_co_u32_e32 v61, vcc, 0, v151, vcc
	v_cvt_pk_bf16_f32 v48, v48, v49
	v_cvt_pk_bf16_f32 v49, v50, v51
	v_cvt_pk_bf16_f32 v50, v44, v45
	v_cvt_pk_bf16_f32 v51, v46, v47
	s_mov_b32 s7, 0x90000
	v_cvt_pk_bf16_f32 v112, v112, v113
	v_cvt_pk_bf16_f32 v113, v114, v115
	v_cvt_pk_bf16_f32 v114, v108, v109
	v_or_b32_e32 v108, 16, v146
	global_store_dwordx4 v[68:69], v[48:51], off offset:64
	s_mov_b64 s[14:15], 0x90000
	v_ashrrev_i32_e32 v109, 31, v108
	v_add_co_u32_e32 v50, vcc, s7, v150
	v_cvt_pk_bf16_f32 v96, v96, v97
	v_cvt_pk_bf16_f32 v97, v98, v99
	v_cvt_pk_bf16_f32 v98, v92, v93
	v_or_b32_e32 v92, 32, v146
	v_lshl_add_u64 v[48:49], v[150:151], 0, s[14:15]
	v_addc_co_u32_e32 v51, vcc, 0, v151, vcc
	v_cvt_pk_bf16_f32 v32, v32, v33
	v_cvt_pk_bf16_f32 v33, v34, v35
	v_cvt_pk_bf16_f32 v34, v28, v29
	v_cvt_pk_bf16_f32 v35, v30, v31
	s_mov_b32 s7, 0xa0000
	v_lshlrev_b64 v[108:109], 12, v[108:109]
	v_ashrrev_i32_e32 v93, 31, v92
	v_cvt_pk_bf16_f32 v80, v80, v81
	v_cvt_pk_bf16_f32 v81, v82, v83
	v_cvt_pk_bf16_f32 v82, v76, v77
	v_or_b32_e32 v76, 48, v146
	global_store_dwordx4 v[48:49], v[32:35], off offset:64
	s_mov_b64 s[14:15], 0xa0000
	v_cvt_pk_bf16_f32 v115, v110, v111
	v_add_co_u32_e32 v34, vcc, s7, v150
	v_lshl_add_u64 v[108:109], s[4:5], 0, v[108:109]
	v_lshlrev_b64 v[92:93], 12, v[92:93]
	v_ashrrev_i32_e32 v77, 31, v76
	v_lshl_add_u64 v[32:33], v[150:151], 0, s[14:15]
	v_addc_co_u32_e32 v35, vcc, 0, v151, vcc
	v_cvt_pk_bf16_f32 v16, v16, v17
	v_cvt_pk_bf16_f32 v17, v18, v19
	v_cvt_pk_bf16_f32 v18, v12, v13
	v_cvt_pk_bf16_f32 v19, v14, v15
	s_mov_b32 s7, 0xb0000
	global_store_dwordx4 v[150:151], v[112:115], off offset:64
	v_cvt_pk_bf16_f32 v99, v94, v95
	v_lshl_add_u64 v[92:93], s[4:5], 0, v[92:93]
	v_lshl_add_u64 v[112:113], v[108:109], 0, v[148:149]
	v_lshlrev_b64 v[76:77], 12, v[76:77]
	global_store_dwordx4 v[32:33], v[16:19], off offset:64
	global_store_dwordx4 v[112:113], v[96:99], off offset:64
	v_cvt_pk_bf16_f32 v83, v78, v79
	v_add_co_u32_e32 v18, vcc, s7, v150
	v_lshl_add_u64 v[96:97], v[92:93], 0, v[148:149]
	v_lshl_add_u64 v[76:77], s[4:5], 0, v[76:77]
	s_mov_b64 s[14:15], 0xb0000
	v_addc_co_u32_e32 v19, vcc, 0, v151, vcc
	v_cvt_pk_bf16_f32 v128, v128, v129
	v_cvt_pk_bf16_f32 v129, v130, v131
	v_cvt_pk_bf16_f32 v130, v124, v125
	v_cvt_pk_bf16_f32 v131, v126, v127
	v_cvt_pk_bf16_f32 v108, v120, v121
	v_cvt_pk_bf16_f32 v109, v122, v123
	v_cvt_pk_bf16_f32 v110, v116, v117
	v_cvt_pk_bf16_f32 v111, v118, v119
	v_cvt_pk_bf16_f32 v92, v104, v105
	v_cvt_pk_bf16_f32 v93, v106, v107
	v_cvt_pk_bf16_f32 v94, v100, v101
	v_cvt_pk_bf16_f32 v95, v102, v103
	global_store_dwordx4 v[96:97], v[80:83], off offset:64
	v_cvt_pk_bf16_f32 v78, v84, v85
	v_cvt_pk_bf16_f32 v79, v86, v87
	v_lshl_add_u64 v[80:81], v[76:77], 0, v[148:149]
	v_cvt_pk_bf16_f32 v76, v88, v89
	v_cvt_pk_bf16_f32 v77, v90, v91
	v_cvt_pk_bf16_f32 v75, v70, v71
	v_cvt_pk_bf16_f32 v67, v62, v63
	v_cvt_pk_bf16_f32 v44, v56, v57
	v_cvt_pk_bf16_f32 v45, v58, v59
	v_cvt_pk_bf16_f32 v46, v52, v53
	v_cvt_pk_bf16_f32 v47, v54, v55
	v_cvt_pk_bf16_f32 v28, v40, v41
	v_cvt_pk_bf16_f32 v29, v42, v43
	v_cvt_pk_bf16_f32 v30, v36, v37
	v_cvt_pk_bf16_f32 v31, v38, v39
	v_lshl_add_u64 v[16:17], v[150:151], 0, s[14:15]
	v_cvt_pk_bf16_f32 v12, v24, v25
	v_cvt_pk_bf16_f32 v13, v26, v27
	v_cvt_pk_bf16_f32 v14, v20, v21
	v_cvt_pk_bf16_f32 v15, v22, v23
	v_cvt_pk_bf16_f32 v8, v8, v9
	v_cvt_pk_bf16_f32 v9, v10, v11
	v_cvt_pk_bf16_f32 v10, v4, v5
	v_cvt_pk_bf16_f32 v11, v6, v7
	s_and_b64 vcc, exec, s[0:1]
	s_mov_b32 s34, s6
	s_mov_b32 s35, s8
	s_mov_b64 s[16:17], s[12:13]
	s_mov_b64 s[14:15], s[10:11]
	global_store_dwordx4 v[150:151], v[128:131], off
	global_store_dwordx4 v[112:113], v[108:111], off
	global_store_dwordx4 v[96:97], v[92:95], off
	global_store_dwordx4 v[80:81], v[76:79], off
	global_store_dwordx4 v[80:81], v[72:75], off offset:64
	global_store_dwordx4 v[60:61], v[64:67], off
	global_store_dwordx4 v[50:51], v[44:47], off
	global_store_dwordx4 v[34:35], v[28:31], off
	global_store_dwordx4 v[18:19], v[12:15], off
	global_store_dwordx4 v[16:17], v[8:11], off offset:64
	s_cbranch_vccz .LBB0_233
	s_waitcnt vmcnt(0)
	s_cmpk_gt_u32 s20, 0xff
	s_cbranch_scc1 .LBB0_240
	s_barrier

.LBB0_816:
	s_add_u32 s18, s16, 0x100
	s_addc_u32 s19, s17, 0
	s_cmpk_eq_i32 s14, 0x2e00
	s_cselect_b32 s23, s1, s19
	s_cselect_b32 s22, s0, s18
	s_cselect_b32 s21, s7, s42
	s_cselect_b32 s20, s6, s41
	s_add_i32 s33, 0, 0x10000
	v_add_u32_e32 v2, s33, v200
	ds_read_b128 v[62:65], v2
	ds_read_b128 v[74:77], v2 offset:1024
	ds_read_b128 v[82:85], v2 offset:2048
	ds_read_b128 v[94:97], v2 offset:3072
	s_add_i32 m0, s30, 0xc000
	ds_read_b128 v[106:109], v202
	ds_read_b128 v[118:121], v202 offset:1024
	ds_read_b128 v[130:133], v202 offset:2048
	ds_read_b128 v[142:145], v202 offset:3072
	ds_read_b128 v[150:153], v202 offset:4096
	ds_read_b128 v[162:165], v202 offset:5120
	ds_read_b128 v[174:177], v202 offset:6144
	ds_read_b128 v[178:181], v202 offset:7168
	global_load_lds_dwordx4 v212, s[16:17]
	s_add_i32 m0, s30, 0xe000
	s_nop 0
	global_load_lds_dwordx4 v214, s[16:17]
	s_waitcnt lgkmcnt(8)
	s_setprio 1
	s_barrier
	s_waitcnt lgkmcnt(0)
	v_mfma_f32_16x16x32_bf16 v[170:173], v[62:65], v[106:109], v[170:173]
	v_mfma_f32_16x16x32_bf16 v[170:173], v[74:77], v[118:121], v[170:173]
	v_mfma_f32_16x16x32_bf16 v[146:149], v[74:77], v[142:145], v[146:149]
	v_mfma_f32_16x16x32_bf16 v[146:149], v[62:65], v[130:133], v[146:149]
	v_mfma_f32_16x16x32_bf16 v[122:125], v[62:65], v[150:153], v[122:125]
	v_mfma_f32_16x16x32_bf16 v[122:125], v[74:77], v[162:165], v[122:125]
	v_mfma_f32_16x16x32_bf16 v[98:101], v[74:77], v[178:181], v[98:101]
	v_mfma_f32_16x16x32_bf16 v[98:101], v[62:65], v[174:177], v[98:101]
	v_mfma_f32_16x16x32_bf16 v[90:93], v[82:85], v[174:177], v[90:93]
	v_mfma_f32_16x16x32_bf16 v[90:93], v[94:97], v[178:181], v[90:93]
	v_mfma_f32_16x16x32_bf16 v[114:117], v[94:97], v[162:165], v[114:117]
	v_mfma_f32_16x16x32_bf16 v[114:117], v[82:85], v[150:153], v[114:117]
	v_mfma_f32_16x16x32_bf16 v[138:141], v[82:85], v[130:133], v[138:141]
	v_mfma_f32_16x16x32_bf16 v[138:141], v[94:97], v[142:145], v[138:141]
	v_mfma_f32_16x16x32_bf16 v[166:169], v[94:97], v[118:121], v[166:169]
	s_setprio 0
	v_mfma_f32_16x16x32_bf16 v[166:169], v[82:85], v[106:109], v[166:169]
	s_barrier
	s_add_i32 s44, 0, 0x14000
	s_add_i32 s16, s33, s29
	v_add_u32_e32 v2, s44, v200
	v_lshl_add_u64 v[226:227], s[20:21], 0, v[208:209]
	s_mov_b32 m0, s16
	ds_read_b128 v[182:185], v2
	ds_read_b128 v[186:189], v2 offset:1024
	ds_read_b128 v[190:193], v2 offset:2048
	ds_read_b128 v[194:197], v2 offset:3072
	global_load_lds_dwordx4 v[226:227], off
	v_lshl_add_u64 v[228:229], s[20:21], 0, v[204:205]
	s_add_i32 m0, s16, 0x2000
	s_nop 0
	global_load_lds_dwordx4 v[228:229], off
	s_setprio 1
	s_barrier
	s_waitcnt lgkmcnt(0)
	v_mfma_f32_16x16x32_bf16 v[158:161], v[182:185], v[106:109], v[158:161]
	v_mfma_f32_16x16x32_bf16 v[158:161], v[186:189], v[118:121], v[158:161]
	v_mfma_f32_16x16x32_bf16 v[106:109], v[190:193], v[106:109], v[154:157]
	v_mfma_f32_16x16x32_bf16 v[106:109], v[194:197], v[118:121], v[106:109]
	v_mfma_f32_16x16x32_bf16 v[126:129], v[190:193], v[130:133], v[126:129]
	v_mfma_f32_16x16x32_bf16 v[126:129], v[194:197], v[142:145], v[126:129]
	v_mfma_f32_16x16x32_bf16 v[110:113], v[182:185], v[150:153], v[110:113]
	v_mfma_f32_16x16x32_bf16 v[110:113], v[186:189], v[162:165], v[110:113]
	v_mfma_f32_16x16x32_bf16 v[102:105], v[190:193], v[150:153], v[102:105]
	v_mfma_f32_16x16x32_bf16 v[102:105], v[194:197], v[162:165], v[102:105]
	v_mfma_f32_16x16x32_bf16 v[86:89], v[182:185], v[174:177], v[86:89]
	v_mfma_f32_16x16x32_bf16 v[86:89], v[186:189], v[178:181], v[86:89]
	v_mfma_f32_16x16x32_bf16 v[78:81], v[190:193], v[174:177], v[78:81]
	v_mfma_f32_16x16x32_bf16 v[78:81], v[194:197], v[178:181], v[78:81]
	v_mfma_f32_16x16x32_bf16 v[118:121], v[182:185], v[130:133], v[134:137]
	s_setprio 0
	v_mfma_f32_16x16x32_bf16 v[118:121], v[186:189], v[142:145], v[118:121]
	s_barrier
	s_mov_b32 m0, s30
	v_lshl_add_u64 v[230:231], s[22:23], 0, v[210:211]
	ds_read_b128 v[130:133], v202 offset:16384
	ds_read_b128 v[134:137], v202 offset:17408
	ds_read_b128 v[142:145], v202 offset:18432
	ds_read_b128 v[150:153], v202 offset:19456
	ds_read_b128 v[154:157], v202 offset:20480
	ds_read_b128 v[162:165], v202 offset:21504
	ds_read_b128 v[174:177], v202 offset:22528
	ds_read_b128 v[178:181], v202 offset:23552
	global_load_lds_dwordx4 v[230:231], off
	v_lshl_add_u64 v[232:233], s[22:23], 0, v[206:207]
	s_mov_b32 m0, s31
	s_nop 0
	global_load_lds_dwordx4 v[232:233], off
	s_waitcnt vmcnt(10)
	s_setprio 1
	s_barrier
	s_waitcnt lgkmcnt(0)
	v_mfma_f32_16x16x32_bf16 v[70:73], v[62:65], v[130:133], v[70:73]
	v_mfma_f32_16x16x32_bf16 v[70:73], v[74:77], v[134:137], v[70:73]
	v_mfma_f32_16x16x32_bf16 v[50:53], v[74:77], v[150:153], v[50:53]
	v_mfma_f32_16x16x32_bf16 v[50:53], v[62:65], v[142:145], v[50:53]
	v_mfma_f32_16x16x32_bf16 v[34:37], v[62:65], v[154:157], v[34:37]
	v_mfma_f32_16x16x32_bf16 v[34:37], v[74:77], v[162:165], v[34:37]
	v_mfma_f32_16x16x32_bf16 v[18:21], v[74:77], v[178:181], v[18:21]
	v_mfma_f32_16x16x32_bf16 v[18:21], v[62:65], v[174:177], v[18:21]
	v_mfma_f32_16x16x32_bf16 v[14:17], v[82:85], v[174:177], v[14:17]
	v_mfma_f32_16x16x32_bf16 v[14:17], v[94:97], v[178:181], v[14:17]
	v_mfma_f32_16x16x32_bf16 v[30:33], v[94:97], v[162:165], v[30:33]
	v_mfma_f32_16x16x32_bf16 v[30:33], v[82:85], v[154:157], v[30:33]
	v_mfma_f32_16x16x32_bf16 v[46:49], v[82:85], v[142:145], v[46:49]
	v_mfma_f32_16x16x32_bf16 v[46:49], v[94:97], v[150:153], v[46:49]
	v_mfma_f32_16x16x32_bf16 v[66:69], v[94:97], v[134:137], v[66:69]
	s_setprio 0
	v_mfma_f32_16x16x32_bf16 v[66:69], v[82:85], v[130:133], v[66:69]
	s_barrier
	s_add_u32 s16, s20, 0xc0000
	s_addc_u32 s17, s21, 0
	s_add_i32 s33, s44, s29
	s_mov_b32 m0, s33
	s_nop 0
	global_load_lds_dwordx4 v208, s[16:17]
	v_lshl_add_u64 v[4:5], s[16:17], 0, v[204:205]
	s_add_i32 m0, s33, 0x2000
	s_nop 0
	global_load_lds_dwordx4 v[4:5], off
	s_add_i32 s33, 0, 0x18000
	v_add_u32_e32 v2, s33, v200
	ds_read_b128 v[62:65], v2
	ds_read_b128 v[74:77], v2 offset:1024
	ds_read_b128 v[82:85], v2 offset:2048
	ds_read_b128 v[94:97], v2 offset:3072
	s_waitcnt vmcnt(6)
	s_setprio 1
	s_barrier
	v_mfma_f32_16x16x32_bf16 v[58:61], v[182:185], v[130:133], v[58:61]
	v_mfma_f32_16x16x32_bf16 v[58:61], v[186:189], v[134:137], v[58:61]
	v_mfma_f32_16x16x32_bf16 v[42:45], v[186:189], v[150:153], v[42:45]
	v_mfma_f32_16x16x32_bf16 v[42:45], v[182:185], v[142:145], v[42:45]
	v_mfma_f32_16x16x32_bf16 v[26:29], v[182:185], v[154:157], v[26:29]
	v_mfma_f32_16x16x32_bf16 v[26:29], v[186:189], v[162:165], v[26:29]
	v_mfma_f32_16x16x32_bf16 v[10:13], v[186:189], v[178:181], v[10:13]
	v_mfma_f32_16x16x32_bf16 v[10:13], v[182:185], v[174:177], v[10:13]
	v_mfma_f32_16x16x32_bf16 v[4:7], v[190:193], v[174:177], v[6:9]
	v_mfma_f32_16x16x32_bf16 v[4:7], v[194:197], v[178:181], v[4:7]
	v_mfma_f32_16x16x32_bf16 v[22:25], v[194:197], v[162:165], v[22:25]
	v_mfma_f32_16x16x32_bf16 v[22:25], v[190:193], v[154:157], v[22:25]
	v_mfma_f32_16x16x32_bf16 v[38:41], v[190:193], v[142:145], v[38:41]
	v_mfma_f32_16x16x32_bf16 v[38:41], v[194:197], v[150:153], v[38:41]
	v_mfma_f32_16x16x32_bf16 v[54:57], v[194:197], v[134:137], v[54:57]
	s_setprio 0
	v_mfma_f32_16x16x32_bf16 v[54:57], v[190:193], v[130:133], v[54:57]
	s_barrier
	s_add_u32 s16, s22, 0xc0000
	s_addc_u32 s17, s23, 0
	s_mov_b32 m0, s34
	v_lshl_add_u64 v[8:9], s[16:17], 0, v[210:211]
	ds_read_b128 v[130:133], v202 offset:32768
	ds_read_b128 v[134:137], v202 offset:33792
	ds_read_b128 v[142:145], v202 offset:34816
	ds_read_b128 v[150:153], v202 offset:35840
	ds_read_b128 v[162:165], v202 offset:36864
	ds_read_b128 v[174:177], v202 offset:37888
	ds_read_b128 v[178:181], v202 offset:38912
	ds_read_b128 v[182:185], v202 offset:39936
	global_load_lds_dwordx4 v[8:9], off
	v_lshl_add_u64 v[8:9], s[16:17], 0, v[206:207]
	s_mov_b32 m0, s35
	s_nop 0
	global_load_lds_dwordx4 v[8:9], off
	s_waitcnt lgkmcnt(8)
	s_setprio 1
	s_barrier
	s_waitcnt lgkmcnt(0)
	v_mfma_f32_16x16x32_bf16 v[154:157], v[62:65], v[130:133], v[170:173]
	v_mfma_f32_16x16x32_bf16 v[170:173], v[74:77], v[134:137], v[154:157]
	v_mfma_f32_16x16x32_bf16 v[154:157], v[82:85], v[130:133], v[166:169]
	v_mfma_f32_16x16x32_bf16 v[166:169], v[94:97], v[134:137], v[154:157]
	v_mfma_f32_16x16x32_bf16 v[146:149], v[62:65], v[142:145], v[146:149]
	v_mfma_f32_16x16x32_bf16 v[146:149], v[74:77], v[150:153], v[146:149]
	v_mfma_f32_16x16x32_bf16 v[138:141], v[82:85], v[142:145], v[138:141]
	v_mfma_f32_16x16x32_bf16 v[138:141], v[94:97], v[150:153], v[138:141]
	v_mfma_f32_16x16x32_bf16 v[122:125], v[62:65], v[162:165], v[122:125]
	v_mfma_f32_16x16x32_bf16 v[122:125], v[74:77], v[174:177], v[122:125]
	v_mfma_f32_16x16x32_bf16 v[114:117], v[82:85], v[162:165], v[114:117]
	v_mfma_f32_16x16x32_bf16 v[114:117], v[94:97], v[174:177], v[114:117]
	v_mfma_f32_16x16x32_bf16 v[98:101], v[62:65], v[178:181], v[98:101]
	v_mfma_f32_16x16x32_bf16 v[98:101], v[74:77], v[182:185], v[98:101]
	v_mfma_f32_16x16x32_bf16 v[90:93], v[82:85], v[178:181], v[90:93]
	s_setprio 0
	v_mfma_f32_16x16x32_bf16 v[90:93], v[94:97], v[182:185], v[90:93]
	s_barrier
	s_add_i32 s22, 0, 0x1c000
	s_add_i32 s16, s33, s29
	v_add_u32_e32 v2, s22, v200
	v_lshl_add_u64 v[8:9], v[226:227], 0, s[2:3]
	s_mov_b32 m0, s16
	ds_read_b128 v[186:189], v2
	ds_read_b128 v[190:193], v2 offset:1024
	ds_read_b128 v[194:197], v2 offset:2048
	ds_read_b128 v[220:223], v2 offset:3072
	global_load_lds_dwordx4 v[8:9], off
	v_lshl_add_u64 v[8:9], v[228:229], 0, s[2:3]
	s_add_i32 m0, s16, 0x2000
	s_nop 0
	global_load_lds_dwordx4 v[8:9], off
	s_setprio 1
	s_barrier
	s_waitcnt lgkmcnt(0)
	v_mfma_f32_16x16x32_bf16 v[154:157], v[186:189], v[130:133], v[158:161]
	v_mfma_f32_16x16x32_bf16 v[158:161], v[190:193], v[134:137], v[154:157]
	v_mfma_f32_16x16x32_bf16 v[106:109], v[194:197], v[130:133], v[106:109]
	v_mfma_f32_16x16x32_bf16 v[154:157], v[220:223], v[134:137], v[106:109]
	v_mfma_f32_16x16x32_bf16 v[106:109], v[186:189], v[142:145], v[118:121]
	v_mfma_f32_16x16x32_bf16 v[134:137], v[190:193], v[150:153], v[106:109]
	v_mfma_f32_16x16x32_bf16 v[106:109], v[194:197], v[142:145], v[126:129]
	v_mfma_f32_16x16x32_bf16 v[126:129], v[220:223], v[150:153], v[106:109]
	v_mfma_f32_16x16x32_bf16 v[106:109], v[186:189], v[162:165], v[110:113]
	v_mfma_f32_16x16x32_bf16 v[110:113], v[190:193], v[174:177], v[106:109]
	v_mfma_f32_16x16x32_bf16 v[102:105], v[194:197], v[162:165], v[102:105]
	v_mfma_f32_16x16x32_bf16 v[102:105], v[220:223], v[174:177], v[102:105]
	v_mfma_f32_16x16x32_bf16 v[86:89], v[186:189], v[178:181], v[86:89]
	v_mfma_f32_16x16x32_bf16 v[86:89], v[190:193], v[182:185], v[86:89]
	v_mfma_f32_16x16x32_bf16 v[78:81], v[194:197], v[178:181], v[78:81]
	s_setprio 0
	v_mfma_f32_16x16x32_bf16 v[78:81], v[220:223], v[182:185], v[78:81]
	s_barrier
	s_mov_b32 m0, s36
	v_lshl_add_u64 v[8:9], v[230:231], 0, s[2:3]
	ds_read_b128 v[106:109], v202 offset:49152
	ds_read_b128 v[118:121], v202 offset:50176
	ds_read_b128 v[130:133], v202 offset:51200
	ds_read_b128 v[142:145], v202 offset:52224
	ds_read_b128 v[150:153], v202 offset:53248
	ds_read_b128 v[162:165], v202 offset:54272
	ds_read_b128 v[174:177], v202 offset:55296
	ds_read_b128 v[178:181], v202 offset:56320
	global_load_lds_dwordx4 v[8:9], off
	v_lshl_add_u64 v[8:9], v[232:233], 0, s[2:3]
	s_mov_b32 m0, s37
	s_nop 0
	global_load_lds_dwordx4 v[8:9], off
	s_setprio 1
	s_barrier
	s_waitcnt lgkmcnt(0)
	v_mfma_f32_16x16x32_bf16 v[70:73], v[62:65], v[106:109], v[70:73]
	v_mfma_f32_16x16x32_bf16 v[70:73], v[74:77], v[118:121], v[70:73]
	v_mfma_f32_16x16x32_bf16 v[50:53], v[74:77], v[142:145], v[50:53]
	v_mfma_f32_16x16x32_bf16 v[50:53], v[62:65], v[130:133], v[50:53]
	v_mfma_f32_16x16x32_bf16 v[34:37], v[62:65], v[150:153], v[34:37]
	v_mfma_f32_16x16x32_bf16 v[34:37], v[74:77], v[162:165], v[34:37]
	v_mfma_f32_16x16x32_bf16 v[18:21], v[74:77], v[178:181], v[18:21]
	v_mfma_f32_16x16x32_bf16 v[18:21], v[62:65], v[174:177], v[18:21]
	v_mfma_f32_16x16x32_bf16 v[14:17], v[82:85], v[174:177], v[14:17]
	v_mfma_f32_16x16x32_bf16 v[14:17], v[94:97], v[178:181], v[14:17]
	v_mfma_f32_16x16x32_bf16 v[30:33], v[94:97], v[162:165], v[30:33]
	v_mfma_f32_16x16x32_bf16 v[30:33], v[82:85], v[150:153], v[30:33]
	v_mfma_f32_16x16x32_bf16 v[46:49], v[82:85], v[130:133], v[46:49]
	v_mfma_f32_16x16x32_bf16 v[46:49], v[94:97], v[142:145], v[46:49]
	v_mfma_f32_16x16x32_bf16 v[66:69], v[94:97], v[118:121], v[66:69]
	s_setprio 0
	v_mfma_f32_16x16x32_bf16 v[66:69], v[82:85], v[106:109], v[66:69]
	s_barrier
	s_add_u32 s16, s20, 0xc0080
	s_addc_u32 s17, s21, 0
	s_add_i32 s20, s22, s29
	v_lshl_add_u64 v[8:9], s[16:17], 0, v[208:209]
	s_mov_b32 m0, s20
	s_nop 0
	global_load_lds_dwordx4 v[8:9], off
	v_lshl_add_u64 v[8:9], s[16:17], 0, v[204:205]
	s_add_i32 m0, s20, 0x2000
	s_nop 0
	global_load_lds_dwordx4 v[8:9], off
	s_waitcnt vmcnt(6)
	s_setprio 1
	s_barrier
	v_mfma_f32_16x16x32_bf16 v[58:61], v[186:189], v[106:109], v[58:61]
	v_mfma_f32_16x16x32_bf16 v[58:61], v[190:193], v[118:121], v[58:61]
	v_mfma_f32_16x16x32_bf16 v[54:57], v[194:197], v[106:109], v[54:57]
	v_mfma_f32_16x16x32_bf16 v[54:57], v[220:223], v[118:121], v[54:57]
	v_mfma_f32_16x16x32_bf16 v[42:45], v[186:189], v[130:133], v[42:45]
	v_mfma_f32_16x16x32_bf16 v[42:45], v[190:193], v[142:145], v[42:45]
	v_mfma_f32_16x16x32_bf16 v[38:41], v[194:197], v[130:133], v[38:41]
	v_mfma_f32_16x16x32_bf16 v[38:41], v[220:223], v[142:145], v[38:41]
	v_mfma_f32_16x16x32_bf16 v[26:29], v[186:189], v[150:153], v[26:29]
	v_mfma_f32_16x16x32_bf16 v[26:29], v[190:193], v[162:165], v[26:29]
	v_mfma_f32_16x16x32_bf16 v[22:25], v[194:197], v[150:153], v[22:25]
	v_mfma_f32_16x16x32_bf16 v[22:25], v[220:223], v[162:165], v[22:25]
	v_mfma_f32_16x16x32_bf16 v[8:11], v[186:189], v[174:177], v[10:13]
	v_mfma_f32_16x16x32_bf16 v[10:13], v[190:193], v[178:181], v[8:11]
	v_mfma_f32_16x16x32_bf16 v[4:7], v[194:197], v[174:177], v[4:7]
	s_setprio 0
	v_mfma_f32_16x16x32_bf16 v[6:9], v[220:223], v[178:181], v[4:7]
	s_barrier
	s_add_u32 s14, s14, 0x200
	s_addc_u32 s15, s15, 0
	s_add_u32 s41, s41, 0x100
	s_addc_u32 s42, s42, 0
	s_cmp_gt_u32 s43, 45
	s_cbranch_scc1 .LBB0_806
	s_mov_b64 s[16:17], s[18:19]
	s_branch .LBB0_814

.LBB0_878:
	s_add_u32 s22, s20, 0xfff80080
	s_addc_u32 s23, s21, -1
	s_add_i32 s49, 0, 0x10000
	s_waitcnt vmcnt(0)
	v_add_u32_e32 v144, s49, v188
	ds_read_b128 v[132:135], v144
	ds_read_b128 v[136:139], v144 offset:1024
	ds_read_b128 v[140:143], v144 offset:2048
	ds_read_b128 v[144:147], v144 offset:3072
	s_cmp_eq_u32 s48, 28
	s_cselect_b32 s25, s15, s23
	s_cselect_b32 s24, s44, s22
	s_cselect_b32 s23, s13, s47
	s_cselect_b32 s22, s45, s46
	s_add_i32 m0, s34, 0xc000
	ds_read_b128 v[148:151], v190
	ds_read_b128 v[152:155], v190 offset:1024
	ds_read_b128 v[156:159], v190 offset:2048
	ds_read_b128 v[160:163], v190 offset:3072
	ds_read_b128 v[174:177], v190 offset:4096
	ds_read_b128 v[178:181], v190 offset:5120
	ds_read_b128 v[182:185], v190 offset:6144
	ds_read_b128 v[192:195], v190 offset:7168
	global_load_lds_dwordx4 v170, s[20:21]
	s_add_i32 m0, s34, 0xe000
	s_nop 0
	global_load_lds_dwordx4 v172, s[20:21]
	s_waitcnt lgkmcnt(8)
	s_setprio 1
	s_barrier
	s_waitcnt lgkmcnt(0)
	v_mfma_f32_16x16x32_bf16 v[128:131], v[132:135], v[148:151], v[128:131]
	v_mfma_f32_16x16x32_bf16 v[128:131], v[136:139], v[152:155], v[128:131]
	v_mfma_f32_16x16x32_bf16 v[120:123], v[136:139], v[160:163], v[120:123]
	v_mfma_f32_16x16x32_bf16 v[120:123], v[132:135], v[156:159], v[120:123]
	v_mfma_f32_16x16x32_bf16 v[96:99], v[132:135], v[174:177], v[96:99]
	v_mfma_f32_16x16x32_bf16 v[96:99], v[136:139], v[178:181], v[96:99]
	v_mfma_f32_16x16x32_bf16 v[88:91], v[136:139], v[192:195], v[88:91]
	v_mfma_f32_16x16x32_bf16 v[88:91], v[132:135], v[182:185], v[88:91]
	v_mfma_f32_16x16x32_bf16 v[84:87], v[140:143], v[182:185], v[84:87]
	v_mfma_f32_16x16x32_bf16 v[84:87], v[144:147], v[192:195], v[84:87]
	v_mfma_f32_16x16x32_bf16 v[92:95], v[144:147], v[178:181], v[92:95]
	v_mfma_f32_16x16x32_bf16 v[92:95], v[140:143], v[174:177], v[92:95]
	v_mfma_f32_16x16x32_bf16 v[116:119], v[140:143], v[156:159], v[116:119]
	v_mfma_f32_16x16x32_bf16 v[116:119], v[144:147], v[160:163], v[116:119]
	v_mfma_f32_16x16x32_bf16 v[124:127], v[144:147], v[152:155], v[124:127]
	s_setprio 0
	v_mfma_f32_16x16x32_bf16 v[124:127], v[140:143], v[148:151], v[124:127]
	s_barrier
	s_add_i32 s52, 0, 0x14000
	v_add_u32_e32 v186, s52, v188
	s_add_i32 s49, s49, s31
	ds_read_b128 v[200:203], v186
	ds_read_b128 v[204:207], v186 offset:1024
	ds_read_b128 v[208:211], v186 offset:2048
	ds_read_b128 v[212:215], v186 offset:3072
	v_lshl_add_u64 v[186:187], s[22:23], 0, v[2:3]
	s_mov_b32 m0, s49
	v_lshl_add_u64 v[196:197], s[22:23], 0, v[164:165]
	global_load_lds_dwordx4 v[186:187], off
	s_add_i32 m0, s49, 0x2000
	s_nop 0
	global_load_lds_dwordx4 v[196:197], off
	s_setprio 1
	s_barrier
	s_waitcnt lgkmcnt(0)
	v_mfma_f32_16x16x32_bf16 v[112:115], v[200:203], v[148:151], v[112:115]
	v_mfma_f32_16x16x32_bf16 v[112:115], v[204:207], v[152:155], v[112:115]
	v_mfma_f32_16x16x32_bf16 v[104:107], v[204:207], v[160:163], v[104:107]
	v_mfma_f32_16x16x32_bf16 v[104:107], v[200:203], v[156:159], v[104:107]
	v_mfma_f32_16x16x32_bf16 v[80:83], v[200:203], v[174:177], v[80:83]
	v_mfma_f32_16x16x32_bf16 v[80:83], v[204:207], v[178:181], v[80:83]
	v_mfma_f32_16x16x32_bf16 v[72:75], v[204:207], v[192:195], v[72:75]
	v_mfma_f32_16x16x32_bf16 v[72:75], v[200:203], v[182:185], v[72:75]
	v_mfma_f32_16x16x32_bf16 v[68:71], v[208:211], v[182:185], v[68:71]
	v_mfma_f32_16x16x32_bf16 v[68:71], v[212:215], v[192:195], v[68:71]
	v_mfma_f32_16x16x32_bf16 v[76:79], v[212:215], v[178:181], v[76:79]
	v_mfma_f32_16x16x32_bf16 v[76:79], v[208:211], v[174:177], v[76:79]
	v_mfma_f32_16x16x32_bf16 v[100:103], v[208:211], v[156:159], v[100:103]
	v_mfma_f32_16x16x32_bf16 v[100:103], v[212:215], v[160:163], v[100:103]
	v_mfma_f32_16x16x32_bf16 v[108:111], v[212:215], v[152:155], v[108:111]
	s_setprio 0
	v_mfma_f32_16x16x32_bf16 v[108:111], v[208:211], v[148:151], v[108:111]
	s_barrier
	s_mov_b32 m0, s34
	v_lshl_add_u64 v[216:217], s[24:25], 0, v[168:169]
	ds_read_b128 v[148:151], v190 offset:16384
	ds_read_b128 v[152:155], v190 offset:17408
	ds_read_b128 v[156:159], v190 offset:18432
	ds_read_b128 v[160:163], v190 offset:19456
	ds_read_b128 v[174:177], v190 offset:20480
	ds_read_b128 v[178:181], v190 offset:21504
	ds_read_b128 v[182:185], v190 offset:22528
	ds_read_b128 v[192:195], v190 offset:23552
	global_load_lds_dwordx4 v[216:217], off
	v_lshl_add_u64 v[218:219], s[24:25], 0, v[166:167]
	s_mov_b32 m0, s35
	s_nop 0
	global_load_lds_dwordx4 v[218:219], off
	s_waitcnt vmcnt(10)
	s_setprio 1
	s_barrier
	s_waitcnt lgkmcnt(0)
	v_mfma_f32_16x16x32_bf16 v[64:67], v[132:135], v[148:151], v[64:67]
	v_mfma_f32_16x16x32_bf16 v[64:67], v[136:139], v[152:155], v[64:67]
	v_mfma_f32_16x16x32_bf16 v[56:59], v[136:139], v[160:163], v[56:59]
	v_mfma_f32_16x16x32_bf16 v[56:59], v[132:135], v[156:159], v[56:59]
	v_mfma_f32_16x16x32_bf16 v[32:35], v[132:135], v[174:177], v[32:35]
	v_mfma_f32_16x16x32_bf16 v[32:35], v[136:139], v[178:181], v[32:35]
	v_mfma_f32_16x16x32_bf16 v[24:27], v[136:139], v[192:195], v[24:27]
	v_mfma_f32_16x16x32_bf16 v[24:27], v[132:135], v[182:185], v[24:27]
	v_mfma_f32_16x16x32_bf16 v[20:23], v[140:143], v[182:185], v[20:23]
	v_mfma_f32_16x16x32_bf16 v[20:23], v[144:147], v[192:195], v[20:23]
	v_mfma_f32_16x16x32_bf16 v[28:31], v[144:147], v[178:181], v[28:31]
	v_mfma_f32_16x16x32_bf16 v[28:31], v[140:143], v[174:177], v[28:31]
	v_mfma_f32_16x16x32_bf16 v[52:55], v[140:143], v[156:159], v[52:55]
	v_mfma_f32_16x16x32_bf16 v[52:55], v[144:147], v[160:163], v[52:55]
	v_mfma_f32_16x16x32_bf16 v[60:63], v[144:147], v[152:155], v[60:63]
	s_setprio 0
	v_mfma_f32_16x16x32_bf16 v[60:63], v[140:143], v[148:151], v[60:63]
	s_barrier
	s_add_u32 s50, s22, 0x80000
	s_addc_u32 s51, s23, 0
	s_add_i32 s49, s52, s31
	v_lshl_add_u64 v[132:133], s[50:51], 0, v[2:3]
	s_mov_b32 m0, s49
	s_nop 0
	global_load_lds_dwordx4 v[132:133], off
	v_lshl_add_u64 v[132:133], s[50:51], 0, v[164:165]
	s_add_i32 m0, s49, 0x2000
	s_nop 0
	global_load_lds_dwordx4 v[132:133], off
	s_add_i32 s49, 0, 0x18000
	v_add_u32_e32 v144, s49, v188
	ds_read_b128 v[132:135], v144
	ds_read_b128 v[136:139], v144 offset:1024
	ds_read_b128 v[140:143], v144 offset:2048
	ds_read_b128 v[144:147], v144 offset:3072
	s_waitcnt vmcnt(6)
	s_setprio 1
	s_barrier
	v_mfma_f32_16x16x32_bf16 v[48:51], v[200:203], v[148:151], v[48:51]
	v_mfma_f32_16x16x32_bf16 v[48:51], v[204:207], v[152:155], v[48:51]
	v_mfma_f32_16x16x32_bf16 v[40:43], v[204:207], v[160:163], v[40:43]
	v_mfma_f32_16x16x32_bf16 v[40:43], v[200:203], v[156:159], v[40:43]
	v_mfma_f32_16x16x32_bf16 v[16:19], v[200:203], v[174:177], v[16:19]
	v_mfma_f32_16x16x32_bf16 v[16:19], v[204:207], v[178:181], v[16:19]
	v_mfma_f32_16x16x32_bf16 v[8:11], v[204:207], v[192:195], v[8:11]
	v_mfma_f32_16x16x32_bf16 v[8:11], v[200:203], v[182:185], v[8:11]
	v_mfma_f32_16x16x32_bf16 v[4:7], v[208:211], v[182:185], v[4:7]
	v_mfma_f32_16x16x32_bf16 v[4:7], v[212:215], v[192:195], v[4:7]
	v_mfma_f32_16x16x32_bf16 v[12:15], v[212:215], v[178:181], v[12:15]
	v_mfma_f32_16x16x32_bf16 v[12:15], v[208:211], v[174:177], v[12:15]
	v_mfma_f32_16x16x32_bf16 v[36:39], v[208:211], v[156:159], v[36:39]
	v_mfma_f32_16x16x32_bf16 v[36:39], v[212:215], v[160:163], v[36:39]
	v_mfma_f32_16x16x32_bf16 v[44:47], v[212:215], v[152:155], v[44:47]
	s_setprio 0
	v_mfma_f32_16x16x32_bf16 v[44:47], v[208:211], v[148:151], v[44:47]
	s_barrier
	s_add_u32 s24, s24, 0x80000
	s_addc_u32 s25, s25, 0
	s_mov_b32 m0, s36
	v_lshl_add_u64 v[200:201], s[24:25], 0, v[168:169]
	ds_read_b128 v[148:151], v190 offset:32768
	ds_read_b128 v[152:155], v190 offset:33792
	ds_read_b128 v[156:159], v190 offset:34816
	ds_read_b128 v[160:163], v190 offset:35840
	ds_read_b128 v[174:177], v190 offset:36864
	ds_read_b128 v[178:181], v190 offset:37888
	ds_read_b128 v[182:185], v190 offset:38912
	ds_read_b128 v[192:195], v190 offset:39936
	global_load_lds_dwordx4 v[200:201], off
	v_lshl_add_u64 v[200:201], s[24:25], 0, v[166:167]
	s_mov_b32 m0, s37
	s_nop 0
	global_load_lds_dwordx4 v[200:201], off
	s_waitcnt lgkmcnt(8)
	s_setprio 1
	s_barrier
	s_waitcnt lgkmcnt(0)
	v_mfma_f32_16x16x32_bf16 v[128:131], v[132:135], v[148:151], v[128:131]
	v_mfma_f32_16x16x32_bf16 v[128:131], v[136:139], v[152:155], v[128:131]
	v_mfma_f32_16x16x32_bf16 v[120:123], v[136:139], v[160:163], v[120:123]
	v_mfma_f32_16x16x32_bf16 v[120:123], v[132:135], v[156:159], v[120:123]
	v_mfma_f32_16x16x32_bf16 v[96:99], v[132:135], v[174:177], v[96:99]
	v_mfma_f32_16x16x32_bf16 v[96:99], v[136:139], v[178:181], v[96:99]
	v_mfma_f32_16x16x32_bf16 v[88:91], v[136:139], v[192:195], v[88:91]
	v_mfma_f32_16x16x32_bf16 v[88:91], v[132:135], v[182:185], v[88:91]
	v_mfma_f32_16x16x32_bf16 v[84:87], v[140:143], v[182:185], v[84:87]
	v_mfma_f32_16x16x32_bf16 v[84:87], v[144:147], v[192:195], v[84:87]
	v_mfma_f32_16x16x32_bf16 v[92:95], v[144:147], v[178:181], v[92:95]
	v_mfma_f32_16x16x32_bf16 v[92:95], v[140:143], v[174:177], v[92:95]
	v_mfma_f32_16x16x32_bf16 v[116:119], v[140:143], v[156:159], v[116:119]
	v_mfma_f32_16x16x32_bf16 v[116:119], v[144:147], v[160:163], v[116:119]
	v_mfma_f32_16x16x32_bf16 v[124:127], v[144:147], v[152:155], v[124:127]
	s_setprio 0
	v_mfma_f32_16x16x32_bf16 v[124:127], v[140:143], v[148:151], v[124:127]
	s_barrier
	s_add_i32 s24, 0, 0x1c000
	s_add_i32 s25, s49, s31
	v_add_u32_e32 v191, s24, v188
	v_lshl_add_u64 v[186:187], v[186:187], 0, s[2:3]
	s_mov_b32 m0, s25
	ds_read_b128 v[200:203], v191
	ds_read_b128 v[204:207], v191 offset:1024
	ds_read_b128 v[208:211], v191 offset:2048
	ds_read_b128 v[212:215], v191 offset:3072
	global_load_lds_dwordx4 v[186:187], off
	v_lshl_add_u64 v[186:187], v[196:197], 0, s[2:3]
	s_add_i32 m0, s25, 0x2000
	s_nop 0
	global_load_lds_dwordx4 v[186:187], off
	s_setprio 1
	s_barrier
	s_waitcnt lgkmcnt(0)
	v_mfma_f32_16x16x32_bf16 v[112:115], v[200:203], v[148:151], v[112:115]
	v_mfma_f32_16x16x32_bf16 v[112:115], v[204:207], v[152:155], v[112:115]
	v_mfma_f32_16x16x32_bf16 v[104:107], v[204:207], v[160:163], v[104:107]
	v_mfma_f32_16x16x32_bf16 v[104:107], v[200:203], v[156:159], v[104:107]
	v_mfma_f32_16x16x32_bf16 v[80:83], v[200:203], v[174:177], v[80:83]
	v_mfma_f32_16x16x32_bf16 v[80:83], v[204:207], v[178:181], v[80:83]
	v_mfma_f32_16x16x32_bf16 v[72:75], v[204:207], v[192:195], v[72:75]
	v_mfma_f32_16x16x32_bf16 v[72:75], v[200:203], v[182:185], v[72:75]
	v_mfma_f32_16x16x32_bf16 v[68:71], v[208:211], v[182:185], v[68:71]
	v_mfma_f32_16x16x32_bf16 v[68:71], v[212:215], v[192:195], v[68:71]
	v_mfma_f32_16x16x32_bf16 v[76:79], v[212:215], v[178:181], v[76:79]
	v_mfma_f32_16x16x32_bf16 v[76:79], v[208:211], v[174:177], v[76:79]
	v_mfma_f32_16x16x32_bf16 v[100:103], v[208:211], v[156:159], v[100:103]
	v_mfma_f32_16x16x32_bf16 v[100:103], v[212:215], v[160:163], v[100:103]
	v_mfma_f32_16x16x32_bf16 v[108:111], v[212:215], v[152:155], v[108:111]
	s_setprio 0
	v_mfma_f32_16x16x32_bf16 v[108:111], v[208:211], v[148:151], v[108:111]
	s_barrier
	s_mov_b32 m0, s41
	v_lshl_add_u64 v[186:187], v[216:217], 0, s[2:3]
	ds_read_b128 v[148:151], v190 offset:49152
	ds_read_b128 v[152:155], v190 offset:50176
	ds_read_b128 v[156:159], v190 offset:51200
	ds_read_b128 v[160:163], v190 offset:52224
	ds_read_b128 v[174:177], v190 offset:53248
	ds_read_b128 v[178:181], v190 offset:54272
	ds_read_b128 v[182:185], v190 offset:55296
	ds_read_b128 v[192:195], v190 offset:56320
	global_load_lds_dwordx4 v[186:187], off
	v_lshl_add_u64 v[186:187], v[218:219], 0, s[2:3]
	s_mov_b32 m0, s42
	s_nop 0
	global_load_lds_dwordx4 v[186:187], off
	s_setprio 1
	s_barrier
	s_waitcnt lgkmcnt(0)
	v_mfma_f32_16x16x32_bf16 v[64:67], v[132:135], v[148:151], v[64:67]
	v_mfma_f32_16x16x32_bf16 v[64:67], v[136:139], v[152:155], v[64:67]
	v_mfma_f32_16x16x32_bf16 v[56:59], v[136:139], v[160:163], v[56:59]
	v_mfma_f32_16x16x32_bf16 v[56:59], v[132:135], v[156:159], v[56:59]
	v_mfma_f32_16x16x32_bf16 v[32:35], v[132:135], v[174:177], v[32:35]
	v_mfma_f32_16x16x32_bf16 v[32:35], v[136:139], v[178:181], v[32:35]
	v_mfma_f32_16x16x32_bf16 v[24:27], v[136:139], v[192:195], v[24:27]
	v_mfma_f32_16x16x32_bf16 v[24:27], v[132:135], v[182:185], v[24:27]
	v_mfma_f32_16x16x32_bf16 v[20:23], v[140:143], v[182:185], v[20:23]
	v_mfma_f32_16x16x32_bf16 v[20:23], v[144:147], v[192:195], v[20:23]
	v_mfma_f32_16x16x32_bf16 v[28:31], v[144:147], v[178:181], v[28:31]
	v_mfma_f32_16x16x32_bf16 v[28:31], v[140:143], v[174:177], v[28:31]
	v_mfma_f32_16x16x32_bf16 v[52:55], v[140:143], v[156:159], v[52:55]
	v_mfma_f32_16x16x32_bf16 v[52:55], v[144:147], v[160:163], v[52:55]
	v_mfma_f32_16x16x32_bf16 v[60:63], v[144:147], v[152:155], v[60:63]
	s_setprio 0
	v_mfma_f32_16x16x32_bf16 v[60:63], v[140:143], v[148:151], v[60:63]
	s_barrier
	s_add_u32 s22, s22, 0x80080
	s_addc_u32 s23, s23, 0
	s_add_i32 s24, s24, s31
	v_lshl_add_u64 v[132:133], s[22:23], 0, v[2:3]
	s_mov_b32 m0, s24
	s_nop 0
	global_load_lds_dwordx4 v[132:133], off
	v_lshl_add_u64 v[132:133], s[22:23], 0, v[164:165]
	s_add_i32 m0, s24, 0x2000
	s_nop 0
	global_load_lds_dwordx4 v[132:133], off
	s_waitcnt vmcnt(6)
	s_setprio 1
	s_barrier
	v_mfma_f32_16x16x32_bf16 v[48:51], v[200:203], v[148:151], v[48:51]
	v_mfma_f32_16x16x32_bf16 v[48:51], v[204:207], v[152:155], v[48:51]
	v_mfma_f32_16x16x32_bf16 v[40:43], v[204:207], v[160:163], v[40:43]
	v_mfma_f32_16x16x32_bf16 v[40:43], v[200:203], v[156:159], v[40:43]
	v_mfma_f32_16x16x32_bf16 v[16:19], v[200:203], v[174:177], v[16:19]
	v_mfma_f32_16x16x32_bf16 v[16:19], v[204:207], v[178:181], v[16:19]
	v_mfma_f32_16x16x32_bf16 v[8:11], v[204:207], v[192:195], v[8:11]
	v_mfma_f32_16x16x32_bf16 v[8:11], v[200:203], v[182:185], v[8:11]
	v_mfma_f32_16x16x32_bf16 v[4:7], v[208:211], v[182:185], v[4:7]
	v_mfma_f32_16x16x32_bf16 v[4:7], v[212:215], v[192:195], v[4:7]
	v_mfma_f32_16x16x32_bf16 v[12:15], v[212:215], v[178:181], v[12:15]
	v_mfma_f32_16x16x32_bf16 v[12:15], v[208:211], v[174:177], v[12:15]
	v_mfma_f32_16x16x32_bf16 v[36:39], v[208:211], v[156:159], v[36:39]
	v_mfma_f32_16x16x32_bf16 v[36:39], v[212:215], v[160:163], v[36:39]
	v_mfma_f32_16x16x32_bf16 v[44:47], v[212:215], v[152:155], v[44:47]
	s_setprio 0
	v_mfma_f32_16x16x32_bf16 v[44:47], v[208:211], v[148:151], v[44:47]
	s_barrier
	s_add_i32 s48, s48, 2
	s_add_u32 s20, s20, 0x100
	s_addc_u32 s21, s21, 0
	s_add_u32 s46, s46, 0x100
	s_addc_u32 s47, s47, 0
	s_cmp_gt_u32 s48, 29
	s_cbranch_scc0 .LBB0_878
	s_cmp_lt_i32 s43, 32
	s_mov_b64 s[20:21], 0
	s_cbranch_scc1 .LBB0_881
	s_sub_i32 s13, s43, 32
	s_lshr_b32 s13, s13, 4
	s_add_i32 s13, s13, 1
	s_mul_hi_u32 s21, s13, 0x3000
	s_mul_i32 s20, s13, 0x3000

.LBB0_1002:
	s_add_u32 s28, s26, 0x100
	s_addc_u32 s29, s27, 0
	s_add_i32 s58, 0, 0x10000
	v_add_u32_e32 v56, s58, v1
	ds_read_b128 v[44:47], v56
	ds_read_b128 v[48:51], v56 offset:1024
	ds_read_b128 v[52:55], v56 offset:2048
	ds_read_b128 v[56:59], v56 offset:3072
	s_cmp_eq_u32 s57, 28
	s_cselect_b32 s35, s21, s29
	s_cselect_b32 s34, s53, s28
	s_cselect_b32 s31, s19, s56
	s_cselect_b32 s30, s54, s55
	v_lshl_add_u64 v[190:191], s[26:27], 0, v[178:179]
	s_add_i32 m0, s42, 0xc000
	ds_read_b128 v[68:71], v200
	ds_read_b128 v[72:75], v200 offset:1024
	ds_read_b128 v[76:79], v200 offset:2048
	ds_read_b128 v[80:83], v200 offset:3072
	ds_read_b128 v[164:167], v200 offset:4096
	ds_read_b128 v[168:171], v200 offset:5120
	ds_read_b128 v[182:185], v200 offset:6144
	ds_read_b128 v[186:189], v200 offset:7168
	global_load_lds_dwordx4 v[190:191], off
	v_lshl_add_u64 v[190:191], s[26:27], 0, v[180:181]
	s_add_i32 m0, s42, 0xe000
	s_nop 0
	global_load_lds_dwordx4 v[190:191], off
	s_waitcnt lgkmcnt(8)
	s_setprio 1
	s_barrier
	s_waitcnt lgkmcnt(0)
	v_mfma_f32_16x16x32_bf16 v[160:163], v[44:47], v[68:71], v[160:163]
	v_mfma_f32_16x16x32_bf16 v[160:163], v[48:51], v[72:75], v[160:163]
	v_mfma_f32_16x16x32_bf16 v[148:151], v[48:51], v[80:83], v[148:151]
	v_mfma_f32_16x16x32_bf16 v[148:151], v[44:47], v[76:79], v[148:151]
	v_mfma_f32_16x16x32_bf16 v[132:135], v[44:47], v[164:167], v[132:135]
	v_mfma_f32_16x16x32_bf16 v[132:135], v[48:51], v[168:171], v[132:135]
	v_mfma_f32_16x16x32_bf16 v[116:119], v[48:51], v[186:189], v[116:119]
	v_mfma_f32_16x16x32_bf16 v[116:119], v[44:47], v[182:185], v[116:119]
	v_mfma_f32_16x16x32_bf16 v[108:111], v[52:55], v[182:185], v[108:111]
	v_mfma_f32_16x16x32_bf16 v[108:111], v[56:59], v[186:189], v[108:111]
	v_mfma_f32_16x16x32_bf16 v[124:127], v[56:59], v[168:171], v[124:127]
	v_mfma_f32_16x16x32_bf16 v[124:127], v[52:55], v[164:167], v[124:127]
	v_mfma_f32_16x16x32_bf16 v[140:143], v[52:55], v[76:79], v[140:143]
	v_mfma_f32_16x16x32_bf16 v[140:143], v[56:59], v[80:83], v[140:143]
	v_mfma_f32_16x16x32_bf16 v[156:159], v[56:59], v[72:75], v[156:159]
	s_setprio 0
	v_mfma_f32_16x16x32_bf16 v[156:159], v[52:55], v[68:71], v[156:159]
	s_barrier
	s_add_i32 s59, 0, 0x14000
	v_add_u32_e32 v194, s59, v1
	s_add_i32 s26, s58, s41
	ds_read_b128 v[190:193], v194
	ds_read_b128 v[202:205], v194 offset:1024
	ds_read_b128 v[206:209], v194 offset:2048
	ds_read_b128 v[210:213], v194 offset:3072
	v_lshl_add_u64 v[194:195], s[30:31], 0, v[2:3]
	s_mov_b32 m0, s26
	v_lshl_add_u64 v[222:223], s[30:31], 0, v[172:173]
	global_load_lds_dwordx4 v[194:195], off
	s_add_i32 m0, s26, 0x2000
	s_nop 0
	global_load_lds_dwordx4 v[222:223], off
	s_setprio 1
	s_barrier
	s_waitcnt lgkmcnt(0)
	v_mfma_f32_16x16x32_bf16 v[152:155], v[190:193], v[68:71], v[152:155]
	v_mfma_f32_16x16x32_bf16 v[152:155], v[202:205], v[72:75], v[152:155]
	v_mfma_f32_16x16x32_bf16 v[68:71], v[206:209], v[68:71], v[144:147]
	v_mfma_f32_16x16x32_bf16 v[68:71], v[210:213], v[72:75], v[68:71]
	v_mfma_f32_16x16x32_bf16 v[72:75], v[190:193], v[76:79], v[136:139]
	v_mfma_f32_16x16x32_bf16 v[72:75], v[202:205], v[80:83], v[72:75]
	v_mfma_f32_16x16x32_bf16 v[76:79], v[206:209], v[76:79], v[128:131]
	v_mfma_f32_16x16x32_bf16 v[76:79], v[210:213], v[80:83], v[76:79]
	v_mfma_f32_16x16x32_bf16 v[112:115], v[206:209], v[164:167], v[112:115]
	v_mfma_f32_16x16x32_bf16 v[112:115], v[210:213], v[168:171], v[112:115]
	v_mfma_f32_16x16x32_bf16 v[104:107], v[190:193], v[182:185], v[104:107]
	v_mfma_f32_16x16x32_bf16 v[104:107], v[202:205], v[186:189], v[104:107]
	v_mfma_f32_16x16x32_bf16 v[96:99], v[206:209], v[182:185], v[96:99]
	v_mfma_f32_16x16x32_bf16 v[96:99], v[210:213], v[186:189], v[96:99]
	v_mfma_f32_16x16x32_bf16 v[80:83], v[190:193], v[164:167], v[120:123]
	s_setprio 0
	v_mfma_f32_16x16x32_bf16 v[80:83], v[202:205], v[168:171], v[80:83]
	s_barrier
	s_mov_b32 m0, s42
	v_lshl_add_u64 v[224:225], s[34:35], 0, v[176:177]
	ds_read_b128 v[120:123], v200 offset:16384
	ds_read_b128 v[128:131], v200 offset:17408
	ds_read_b128 v[136:139], v200 offset:18432
	ds_read_b128 v[144:147], v200 offset:19456
	ds_read_b128 v[164:167], v200 offset:20480
	ds_read_b128 v[168:171], v200 offset:21504
	ds_read_b128 v[182:185], v200 offset:22528
	ds_read_b128 v[186:189], v200 offset:23552
	global_load_lds_dwordx4 v[224:225], off
	v_lshl_add_u64 v[226:227], s[34:35], 0, v[174:175]
	s_mov_b32 m0, s43
	s_nop 0
	global_load_lds_dwordx4 v[226:227], off
	s_waitcnt vmcnt(10)
	s_setprio 1
	s_barrier
	s_waitcnt lgkmcnt(0)
	v_mfma_f32_16x16x32_bf16 v[100:103], v[44:47], v[120:123], v[100:103]
	v_mfma_f32_16x16x32_bf16 v[100:103], v[48:51], v[128:131], v[100:103]
	v_mfma_f32_16x16x32_bf16 v[84:87], v[48:51], v[144:147], v[84:87]
	v_mfma_f32_16x16x32_bf16 v[84:87], v[44:47], v[136:139], v[84:87]
	v_mfma_f32_16x16x32_bf16 v[36:39], v[44:47], v[164:167], v[36:39]
	v_mfma_f32_16x16x32_bf16 v[36:39], v[48:51], v[168:171], v[36:39]
	v_mfma_f32_16x16x32_bf16 v[16:19], v[48:51], v[186:189], v[16:19]
	v_mfma_f32_16x16x32_bf16 v[16:19], v[44:47], v[182:185], v[16:19]
	v_mfma_f32_16x16x32_bf16 v[12:15], v[52:55], v[182:185], v[12:15]
	v_mfma_f32_16x16x32_bf16 v[12:15], v[56:59], v[186:189], v[12:15]
	v_mfma_f32_16x16x32_bf16 v[28:31], v[56:59], v[168:171], v[28:31]
	v_mfma_f32_16x16x32_bf16 v[28:31], v[52:55], v[164:167], v[28:31]
	v_mfma_f32_16x16x32_bf16 v[60:63], v[52:55], v[136:139], v[60:63]
	v_mfma_f32_16x16x32_bf16 v[60:63], v[56:59], v[144:147], v[60:63]
	v_mfma_f32_16x16x32_bf16 v[92:95], v[56:59], v[128:131], v[92:95]
	s_setprio 0
	v_mfma_f32_16x16x32_bf16 v[92:95], v[52:55], v[120:123], v[92:95]
	s_barrier
	s_add_u32 s26, s30, 0x80000
	s_addc_u32 s27, s31, 0
	s_add_i32 s58, s59, s41
	v_lshl_add_u64 v[44:45], s[26:27], 0, v[2:3]
	s_mov_b32 m0, s58
	s_nop 0
	global_load_lds_dwordx4 v[44:45], off
	v_lshl_add_u64 v[44:45], s[26:27], 0, v[172:173]
	s_add_i32 m0, s58, 0x2000
	s_nop 0
	global_load_lds_dwordx4 v[44:45], off
	s_add_i32 s58, 0, 0x18000
	v_add_u32_e32 v44, s58, v1
	ds_read_b128 v[52:55], v44
	ds_read_b128 v[56:59], v44 offset:1024
	s_waitcnt vmcnt(6)
	s_setprio 1
	s_barrier
	v_mfma_f32_16x16x32_bf16 v[40:43], v[190:193], v[136:139], v[40:43]
	v_mfma_f32_16x16x32_bf16 v[40:43], v[202:205], v[144:147], v[40:43]
	v_mfma_f32_16x16x32_bf16 v[24:27], v[202:205], v[168:171], v[24:27]
	v_mfma_f32_16x16x32_bf16 v[24:27], v[190:193], v[164:167], v[24:27]
	v_mfma_f32_16x16x32_bf16 v[8:11], v[190:193], v[182:185], v[8:11]
	v_mfma_f32_16x16x32_bf16 v[8:11], v[202:205], v[186:189], v[8:11]
	v_mfma_f32_16x16x32_bf16 v[44:47], v[202:205], v[128:131], v[88:91]
	v_mfma_f32_16x16x32_bf16 v[44:47], v[190:193], v[120:123], v[44:47]
	v_mfma_f32_16x16x32_bf16 v[48:51], v[206:209], v[120:123], v[64:67]
	v_mfma_f32_16x16x32_bf16 v[48:51], v[210:213], v[128:131], v[48:51]
	v_mfma_f32_16x16x32_bf16 v[4:7], v[210:213], v[186:189], v[4:7]
	v_mfma_f32_16x16x32_bf16 v[4:7], v[206:209], v[182:185], v[4:7]
	v_mfma_f32_16x16x32_bf16 v[20:23], v[206:209], v[164:167], v[20:23]
	v_mfma_f32_16x16x32_bf16 v[20:23], v[210:213], v[168:171], v[20:23]
	v_mfma_f32_16x16x32_bf16 v[32:35], v[210:213], v[144:147], v[32:35]
	s_setprio 0
	v_mfma_f32_16x16x32_bf16 v[32:35], v[206:209], v[136:139], v[32:35]
	s_barrier
	v_add_u32_e32 v88, s58, v1
	ds_read_b128 v[64:67], v88 offset:2048
	ds_read_b128 v[88:91], v88 offset:3072
	s_add_u32 s26, s34, 0x4000
	s_addc_u32 s27, s35, 0
	s_mov_b32 m0, s44
	v_lshl_add_u64 v[136:137], s[26:27], 0, v[176:177]
	ds_read_b128 v[120:123], v200 offset:32768
	ds_read_b128 v[128:131], v200 offset:33792
	ds_read_b128 v[164:167], v200 offset:34816
	ds_read_b128 v[168:171], v200 offset:35840
	ds_read_b128 v[182:185], v200 offset:36864
	ds_read_b128 v[186:189], v200 offset:37888
	ds_read_b128 v[190:193], v200 offset:38912
	ds_read_b128 v[202:205], v200 offset:39936
	global_load_lds_dwordx4 v[136:137], off
	v_lshl_add_u64 v[136:137], s[26:27], 0, v[174:175]
	s_mov_b32 m0, s45
	s_nop 0
	global_load_lds_dwordx4 v[136:137], off
	s_waitcnt lgkmcnt(8)
	s_setprio 1
	s_barrier
	s_waitcnt lgkmcnt(0)
	v_mfma_f32_16x16x32_bf16 v[136:139], v[52:55], v[120:123], v[160:163]
	v_mfma_f32_16x16x32_bf16 v[160:163], v[56:59], v[128:131], v[136:139]
	v_mfma_f32_16x16x32_bf16 v[136:139], v[64:67], v[120:123], v[156:159]
	v_mfma_f32_16x16x32_bf16 v[156:159], v[88:91], v[128:131], v[136:139]
	v_mfma_f32_16x16x32_bf16 v[136:139], v[52:55], v[164:167], v[148:151]
	v_mfma_f32_16x16x32_bf16 v[148:151], v[56:59], v[168:171], v[136:139]
	v_mfma_f32_16x16x32_bf16 v[136:139], v[64:67], v[164:167], v[140:143]
	v_mfma_f32_16x16x32_bf16 v[140:143], v[88:91], v[168:171], v[136:139]
	v_mfma_f32_16x16x32_bf16 v[132:135], v[52:55], v[182:185], v[132:135]
	v_mfma_f32_16x16x32_bf16 v[132:135], v[56:59], v[186:189], v[132:135]
	v_mfma_f32_16x16x32_bf16 v[124:127], v[64:67], v[182:185], v[124:127]
	v_mfma_f32_16x16x32_bf16 v[124:127], v[88:91], v[186:189], v[124:127]
	v_mfma_f32_16x16x32_bf16 v[116:119], v[52:55], v[190:193], v[116:119]
	v_mfma_f32_16x16x32_bf16 v[116:119], v[56:59], v[202:205], v[116:119]
	v_mfma_f32_16x16x32_bf16 v[108:111], v[64:67], v[190:193], v[108:111]
	s_setprio 0
	v_mfma_f32_16x16x32_bf16 v[108:111], v[88:91], v[202:205], v[108:111]
	s_barrier
	s_add_i32 s34, 0, 0x1c000
	v_add_u32_e32 v136, s34, v1
	s_add_i32 s26, s58, s41
	ds_read_b128 v[206:209], v136
	ds_read_b128 v[210:213], v136 offset:1024
	ds_read_b128 v[214:217], v136 offset:2048
	ds_read_b128 v[218:221], v136 offset:3072
	v_lshl_add_u64 v[136:137], v[194:195], 0, s[2:3]
	s_mov_b32 m0, s26
	s_nop 0
	global_load_lds_dwordx4 v[136:137], off
	v_lshl_add_u64 v[136:137], v[222:223], 0, s[2:3]
	s_add_i32 m0, s26, 0x2000
	s_nop 0
	global_load_lds_dwordx4 v[136:137], off
	s_setprio 1
	s_barrier
	s_waitcnt lgkmcnt(0)
	v_mfma_f32_16x16x32_bf16 v[68:71], v[214:217], v[120:123], v[68:71]
	v_mfma_f32_16x16x32_bf16 v[144:147], v[218:221], v[128:131], v[68:71]
	v_mfma_f32_16x16x32_bf16 v[136:139], v[206:209], v[120:123], v[152:155]
	v_mfma_f32_16x16x32_bf16 v[152:155], v[210:213], v[128:131], v[136:139]
	v_mfma_f32_16x16x32_bf16 v[68:71], v[206:209], v[164:167], v[72:75]
	v_mfma_f32_16x16x32_bf16 v[136:139], v[210:213], v[168:171], v[68:71]
	v_mfma_f32_16x16x32_bf16 v[68:71], v[214:217], v[164:167], v[76:79]
	v_mfma_f32_16x16x32_bf16 v[128:131], v[218:221], v[168:171], v[68:71]
	v_mfma_f32_16x16x32_bf16 v[68:71], v[206:209], v[182:185], v[80:83]
	v_mfma_f32_16x16x32_bf16 v[120:123], v[210:213], v[186:189], v[68:71]
	v_mfma_f32_16x16x32_bf16 v[68:71], v[214:217], v[182:185], v[112:115]
	v_mfma_f32_16x16x32_bf16 v[112:115], v[218:221], v[186:189], v[68:71]
	v_mfma_f32_16x16x32_bf16 v[68:71], v[206:209], v[190:193], v[104:107]
	v_mfma_f32_16x16x32_bf16 v[104:107], v[210:213], v[202:205], v[68:71]
	v_mfma_f32_16x16x32_bf16 v[68:71], v[214:217], v[190:193], v[96:99]
	s_setprio 0
	v_mfma_f32_16x16x32_bf16 v[96:99], v[218:221], v[202:205], v[68:71]
	s_barrier
	s_mov_b32 m0, s48
	v_lshl_add_u64 v[190:191], v[224:225], 0, s[2:3]
	s_nop 2
	ds_read_b128 v[68:71], v200 offset:49152
	ds_read_b128 v[72:75], v200 offset:50176
	ds_read_b128 v[76:79], v200 offset:51200
	ds_read_b128 v[80:83], v200 offset:52224
	ds_read_b128 v[164:167], v200 offset:53248
	ds_read_b128 v[168:171], v200 offset:54272
	ds_read_b128 v[182:185], v200 offset:55296
	ds_read_b128 v[186:189], v200 offset:56320
	global_load_lds_dwordx4 v[190:191], off
	v_lshl_add_u64 v[190:191], v[226:227], 0, s[2:3]
	s_mov_b32 m0, s49
	s_nop 0
	global_load_lds_dwordx4 v[190:191], off
	s_setprio 1
	s_barrier
	s_waitcnt lgkmcnt(0)
	v_mfma_f32_16x16x32_bf16 v[100:103], v[52:55], v[68:71], v[100:103]
	v_mfma_f32_16x16x32_bf16 v[100:103], v[56:59], v[72:75], v[100:103]
	v_mfma_f32_16x16x32_bf16 v[84:87], v[56:59], v[80:83], v[84:87]
	v_mfma_f32_16x16x32_bf16 v[84:87], v[52:55], v[76:79], v[84:87]
	v_mfma_f32_16x16x32_bf16 v[36:39], v[52:55], v[164:167], v[36:39]
	v_mfma_f32_16x16x32_bf16 v[36:39], v[56:59], v[168:171], v[36:39]
	v_mfma_f32_16x16x32_bf16 v[16:19], v[56:59], v[186:189], v[16:19]
	v_mfma_f32_16x16x32_bf16 v[16:19], v[52:55], v[182:185], v[16:19]
	v_mfma_f32_16x16x32_bf16 v[12:15], v[64:67], v[182:185], v[12:15]
	v_mfma_f32_16x16x32_bf16 v[12:15], v[88:91], v[186:189], v[12:15]
	v_mfma_f32_16x16x32_bf16 v[28:31], v[88:91], v[168:171], v[28:31]
	v_mfma_f32_16x16x32_bf16 v[28:31], v[64:67], v[164:167], v[28:31]
	v_mfma_f32_16x16x32_bf16 v[60:63], v[64:67], v[76:79], v[60:63]
	v_mfma_f32_16x16x32_bf16 v[60:63], v[88:91], v[80:83], v[60:63]
	v_mfma_f32_16x16x32_bf16 v[92:95], v[88:91], v[72:75], v[92:95]
	s_setprio 0
	v_mfma_f32_16x16x32_bf16 v[92:95], v[64:67], v[68:71], v[92:95]
	s_barrier
	s_add_u32 s26, s30, 0x80080
	s_addc_u32 s27, s31, 0
	s_add_i32 s30, s34, s41
	s_mov_b32 m0, s30
	s_nop 0
	global_load_lds_dwordx4 v2, s[26:27]
	s_add_i32 m0, s30, 0x2000
	s_nop 0
	global_load_lds_dwordx4 v172, s[26:27]
	s_waitcnt vmcnt(6)
	s_setprio 1
	s_barrier
	v_mfma_f32_16x16x32_bf16 v[44:47], v[206:209], v[68:71], v[44:47]
	v_mfma_f32_16x16x32_bf16 v[88:91], v[210:213], v[72:75], v[44:47]
	v_mfma_f32_16x16x32_bf16 v[44:47], v[214:217], v[68:71], v[48:51]
	v_mfma_f32_16x16x32_bf16 v[64:67], v[218:221], v[72:75], v[44:47]
	v_mfma_f32_16x16x32_bf16 v[40:43], v[206:209], v[76:79], v[40:43]
	v_mfma_f32_16x16x32_bf16 v[40:43], v[210:213], v[80:83], v[40:43]
	v_mfma_f32_16x16x32_bf16 v[32:35], v[214:217], v[76:79], v[32:35]
	v_mfma_f32_16x16x32_bf16 v[32:35], v[218:221], v[80:83], v[32:35]
	v_mfma_f32_16x16x32_bf16 v[24:27], v[206:209], v[164:167], v[24:27]
	v_mfma_f32_16x16x32_bf16 v[24:27], v[210:213], v[168:171], v[24:27]
	v_mfma_f32_16x16x32_bf16 v[20:23], v[214:217], v[164:167], v[20:23]
	v_mfma_f32_16x16x32_bf16 v[20:23], v[218:221], v[168:171], v[20:23]
	v_mfma_f32_16x16x32_bf16 v[8:11], v[206:209], v[182:185], v[8:11]
	v_mfma_f32_16x16x32_bf16 v[8:11], v[210:213], v[186:189], v[8:11]
	v_mfma_f32_16x16x32_bf16 v[4:7], v[214:217], v[182:185], v[4:7]
	s_setprio 0
	v_mfma_f32_16x16x32_bf16 v[4:7], v[218:221], v[186:189], v[4:7]
	s_barrier
	s_add_i32 s57, s57, 2
	s_add_u32 s55, s55, 0x100
	s_addc_u32 s56, s56, 0
	s_cmp_gt_u32 s57, 29
	s_mov_b64 s[26:27], s[28:29]
	s_cbranch_scc0 .LBB0_1002
	v_lshl_or_b32 v182, s52, 7, v197
	v_ashrrev_i32_e32 v183, 31, v182
	v_lshlrev_b64 v[56:57], 2, v[182:183]
	v_lshl_add_u64 v[48:49], s[10:11], 0, v[56:57]
	global_load_dwordx4 v[44:47], v[48:49], off offset:16
	global_load_dwordx4 v[68:71], v[48:49], off
	v_lshl_add_u64 v[52:53], s[14:15], 0, v[56:57]
	global_load_dwordx4 v[48:51], v[52:53], off offset:16
	global_load_dwordx4 v[72:75], v[52:53], off
	v_lshl_add_u64 v[58:59], s[16:17], 0, v[56:57]
	global_load_dwordx4 v[52:55], v[58:59], off offset:16
	global_load_dwordx4 v[76:79], v[58:59], off
	v_lshl_add_u64 v[80:81], s[12:13], 0, v[56:57]
	global_load_dwordx4 v[56:59], v[80:81], off offset:16
	s_nop 0
	global_load_dwordx4 v[80:83], v[80:81], off
	v_mov_b32_dpp v164, v8 row_shr:1 row_mask:0xf bank_mask:0xf bound_ctrl:1
	v_mov_b32_dpp v165, v9 row_shr:1 row_mask:0xf bank_mask:0xf bound_ctrl:1
	v_mov_b32_dpp v166, v10 row_shr:1 row_mask:0xf bank_mask:0xf bound_ctrl:1
	v_mov_b32_dpp v167, v11 row_shr:1 row_mask:0xf bank_mask:0xf bound_ctrl:1
	v_mov_b32_dpp v168, v4 row_shr:1 row_mask:0xf bank_mask:0xf bound_ctrl:1
	v_mov_b32_dpp v169, v5 row_shr:1 row_mask:0xf bank_mask:0xf bound_ctrl:1
	v_mov_b32_dpp v170, v6 row_shr:1 row_mask:0xf bank_mask:0xf bound_ctrl:1
	v_mov_b32_dpp v171, v7 row_shr:1 row_mask:0xf bank_mask:0xf bound_ctrl:1
	v_lshl_add_u32 v201, s33, 8, v196
	s_movk_i32 s21, 0x2c00
	s_lshl_b32 s19, s33, 2
	v_mov_b32_dpp v190, v152 row_shl:1 row_mask:0xf bank_mask:0xf bound_ctrl:1
	v_mov_b32_dpp v191, v153 row_shl:1 row_mask:0xf bank_mask:0xf bound_ctrl:1
	v_mov_b32_dpp v188, v154 row_shl:1 row_mask:0xf bank_mask:0xf bound_ctrl:1
	v_mov_b32_dpp v189, v155 row_shl:1 row_mask:0xf bank_mask:0xf bound_ctrl:1
	v_mov_b32_dpp v186, v144 row_shl:1 row_mask:0xf bank_mask:0xf bound_ctrl:1
	v_mov_b32_dpp v187, v145 row_shl:1 row_mask:0xf bank_mask:0xf bound_ctrl:1
	v_mov_b32_dpp v184, v146 row_shl:1 row_mask:0xf bank_mask:0xf bound_ctrl:1
	v_mov_b32_dpp v185, v147 row_shl:1 row_mask:0xf bank_mask:0xf bound_ctrl:1
	s_add_i32 s19, s19, s50
	s_waitcnt vmcnt(0)
	v_pk_mul_f32 v[168:169], v[44:45], v[168:169]
	v_pk_mul_f32 v[164:165], v[68:69], v[164:165]
	v_pk_mul_f32 v[166:167], v[70:71], v[166:167]
	v_pk_fma_f32 v[164:165], v[152:153], v[72:73], v[164:165]
	v_pk_fma_f32 v[166:167], v[154:155], v[74:75], v[166:167]
	v_pk_fma_f32 v[164:165], v[136:137], v[76:77], v[164:165]
	v_pk_fma_f32 v[166:167], v[138:139], v[78:79], v[166:167]
	v_pk_add_f32 v[164:165], v[80:81], v[164:165]
	v_pk_add_f32 v[166:167], v[82:83], v[166:167]
	v_mul_f32_e32 v192, 0xbfb8aa3b, v164
	v_mul_f32_e32 v193, 0xbfb8aa3b, v165
	v_exp_f32_e32 v192, v192
	v_exp_f32_e32 v193, v193
	v_pk_fma_f32 v[168:169], v[144:145], v[48:49], v[168:169]
	v_pk_mul_f32 v[170:171], v[46:47], v[170:171]
	v_pk_fma_f32 v[168:169], v[128:129], v[52:53], v[168:169]
	v_pk_add_f32 v[192:193], v[192:193], 1.0 op_sel_hi:[1,0]
	v_pk_add_f32 v[168:169], v[56:57], v[168:169]
	v_rcp_f32_e32 v195, v193
	v_pk_fma_f32 v[170:171], v[146:147], v[50:51], v[170:171]
	v_fma_f32 v202, -v193, v195, 1.0
	v_fmac_f32_e32 v195, v202, v195
	v_div_fixup_f32 v193, v195, v193, 1.0
	v_rcp_f32_e32 v195, v192
	v_pk_fma_f32 v[170:171], v[130:131], v[54:55], v[170:171]
	v_fma_f32 v202, -v192, v195, 1.0
	v_fmac_f32_e32 v195, v202, v195
	v_div_fixup_f32 v192, v195, v192, 1.0
	v_mul_f32_e32 v194, 0xbfb8aa3b, v166
	v_mul_f32_e32 v195, 0xbfb8aa3b, v167
	v_exp_f32_e32 v194, v194
	v_exp_f32_e32 v195, v195
	v_pk_add_f32 v[170:171], v[58:59], v[170:171]
	v_pk_mul_f32 v[192:193], v[164:165], v[192:193]
	v_pk_add_f32 v[194:195], v[194:195], 1.0 op_sel_hi:[1,0]
	s_nop 0
	v_rcp_f32_e32 v203, v195
	v_pk_mul_f32 v[192:193], v[160:161], v[192:193]
	v_fma_f32 v204, -v195, v203, 1.0
	v_fmac_f32_e32 v203, v204, v203
	v_div_fixup_f32 v195, v203, v195, 1.0
	v_rcp_f32_e32 v203, v194
	v_cvt_pk_bf16_f32 v192, v192, v193
	v_fma_f32 v204, -v194, v203, 1.0
	v_fmac_f32_e32 v203, v204, v203
	v_div_fixup_f32 v194, v203, v194, 1.0
	v_mul_f32_e32 v202, 0xbfb8aa3b, v168
	v_mul_f32_e32 v203, 0xbfb8aa3b, v169
	v_exp_f32_e32 v202, v202
	v_exp_f32_e32 v203, v203
	v_pk_mul_f32 v[194:195], v[166:167], v[194:195]
	v_pk_add_f32 v[202:203], v[202:203], 1.0 op_sel_hi:[1,0]
	s_nop 0
	v_rcp_f32_e32 v205, v203
	v_pk_mul_f32 v[194:195], v[162:163], v[194:195]
	v_fma_f32 v206, -v203, v205, 1.0
	v_fmac_f32_e32 v205, v206, v205
	v_div_fixup_f32 v203, v205, v203, 1.0
	v_rcp_f32_e32 v205, v202
	v_cvt_pk_bf16_f32 v193, v194, v195
	v_fma_f32 v206, -v202, v205, 1.0
	v_fmac_f32_e32 v205, v206, v205
	v_div_fixup_f32 v202, v205, v202, 1.0
	v_mul_f32_e32 v204, 0xbfb8aa3b, v170
	v_mul_f32_e32 v205, 0xbfb8aa3b, v171
	v_exp_f32_e32 v204, v204
	v_exp_f32_e32 v205, v205
	v_pk_mul_f32 v[202:203], v[168:169], v[202:203]
	v_pk_add_f32 v[204:205], v[204:205], 1.0 op_sel_hi:[1,0]
	s_nop 0
	v_rcp_f32_e32 v207, v205
	v_pk_mul_f32 v[202:203], v[156:157], v[202:203]
	v_fma_f32 v208, -v205, v207, 1.0
	v_fmac_f32_e32 v207, v208, v207
	v_div_fixup_f32 v205, v207, v205, 1.0
	v_rcp_f32_e32 v207, v204
	v_cvt_pk_bf16_f32 v194, v202, v203
	v_mov_b64_e32 v[202:203], s[0:1]
	v_mad_i64_i32 v[202:203], s[26:27], v201, s21, v[202:203]
	v_fma_f32 v208, -v204, v207, 1.0
	v_fmac_f32_e32 v207, v208, v207
	v_div_fixup_f32 v204, v207, v204, 1.0
	v_pk_mul_f32 v[204:205], v[170:171], v[204:205]
	v_lshl_add_u64 v[202:203], v[182:183], 1, v[202:203]
	v_pk_mul_f32 v[204:205], v[158:159], v[204:205]
	s_nop 0
	v_cvt_pk_bf16_f32 v195, v204, v205
	global_store_dwordx4 v[202:203], v[192:195], off
	s_and_saveexec_b64 s[26:27], s[6:7]
	s_cbranch_execz .LBB0_1005
	s_mul_i32 s28, s19, 0x10800
	s_mul_hi_i32 s21, s19, 0x10800
	s_add_u32 s28, s46, s28
	s_addc_u32 s29, s47, s21
	v_lshl_add_u64 v[192:193], v[182:183], 2, s[28:29]
	global_store_dwordx4 v[192:193], v[164:167], off
	global_store_dwordx4 v[192:193], v[168:171], off offset:16
	s_nop 0
	v_add_co_u32_e32 v164, vcc, 0x5000, v192
	s_nop 1
	v_addc_co_u32_e32 v165, vcc, 0, v193, vcc
	global_store_dwordx4 v[164:165], v[160:163], off offset:2048
	global_store_dwordx4 v[164:165], v[156:159], off offset:2064
	s_nop 1
	v_add_co_u32_e32 v156, vcc, 0xb000, v192
	s_nop 1
	v_addc_co_u32_e32 v157, vcc, 0, v193, vcc
	global_store_dwordx4 v[156:157], v[152:155], off
	global_store_dwordx4 v[156:157], v[144:147], off offset:16

.LBB0_1180:
	s_add_u32 s16, s14, 0x100
	s_addc_u32 s17, s15, 0
	s_add_i32 s45, 0, 0x10000
	v_add_u32_e32 v144, s45, v200
	ds_read_b128 v[132:135], v144
	ds_read_b128 v[136:139], v144 offset:1024
	ds_read_b128 v[140:143], v144 offset:2048
	ds_read_b128 v[144:147], v144 offset:3072
	s_cmpk_eq_i32 s44, 0x54
	s_cselect_b32 s21, s1, s17
	s_cselect_b32 s20, s0, s16
	s_cselect_b32 s19, s7, s43
	s_cselect_b32 s18, s6, s42
	s_add_i32 m0, s28, 0xc000
	ds_read_b128 v[148:151], v202
	ds_read_b128 v[152:155], v202 offset:1024
	ds_read_b128 v[156:159], v202 offset:2048
	ds_read_b128 v[160:163], v202 offset:3072
	ds_read_b128 v[164:167], v202 offset:4096
	ds_read_b128 v[168:171], v202 offset:5120
	ds_read_b128 v[172:175], v202 offset:6144
	ds_read_b128 v[186:189], v202 offset:7168
	global_load_lds_dwordx4 v182, s[14:15]
	s_add_i32 m0, s28, 0xe000
	s_nop 0
	global_load_lds_dwordx4 v184, s[14:15]
	s_waitcnt lgkmcnt(8)
	s_setprio 1
	s_barrier
	s_waitcnt lgkmcnt(0)
	v_mfma_f32_16x16x32_bf16 v[128:131], v[132:135], v[148:151], v[128:131]
	v_mfma_f32_16x16x32_bf16 v[128:131], v[136:139], v[152:155], v[128:131]
	v_mfma_f32_16x16x32_bf16 v[112:115], v[136:139], v[160:163], v[112:115]
	v_mfma_f32_16x16x32_bf16 v[112:115], v[132:135], v[156:159], v[112:115]
	v_mfma_f32_16x16x32_bf16 v[96:99], v[132:135], v[164:167], v[96:99]
	v_mfma_f32_16x16x32_bf16 v[96:99], v[136:139], v[168:171], v[96:99]
	v_mfma_f32_16x16x32_bf16 v[80:83], v[136:139], v[186:189], v[80:83]
	v_mfma_f32_16x16x32_bf16 v[80:83], v[132:135], v[172:175], v[80:83]
	v_mfma_f32_16x16x32_bf16 v[76:79], v[140:143], v[172:175], v[76:79]
	v_mfma_f32_16x16x32_bf16 v[76:79], v[144:147], v[186:189], v[76:79]
	v_mfma_f32_16x16x32_bf16 v[92:95], v[144:147], v[168:171], v[92:95]
	v_mfma_f32_16x16x32_bf16 v[92:95], v[140:143], v[164:167], v[92:95]
	v_mfma_f32_16x16x32_bf16 v[108:111], v[140:143], v[156:159], v[108:111]
	v_mfma_f32_16x16x32_bf16 v[108:111], v[144:147], v[160:163], v[108:111]
	v_mfma_f32_16x16x32_bf16 v[124:127], v[144:147], v[152:155], v[124:127]
	s_setprio 0
	v_mfma_f32_16x16x32_bf16 v[124:127], v[140:143], v[148:151], v[124:127]
	s_barrier
	s_add_i32 s46, 0, 0x14000
	s_add_i32 s14, s45, s27
	v_add_u32_e32 v203, s46, v200
	v_lshl_add_u64 v[212:213], s[18:19], 0, v[2:3]
	s_mov_b32 m0, s14
	ds_read_b128 v[190:193], v203
	ds_read_b128 v[194:197], v203 offset:1024
	ds_read_b128 v[204:207], v203 offset:2048
	ds_read_b128 v[208:211], v203 offset:3072
	global_load_lds_dwordx4 v[212:213], off
	v_lshl_add_u64 v[214:215], s[18:19], 0, v[176:177]
	s_add_i32 m0, s14, 0x2000
	s_nop 0
	global_load_lds_dwordx4 v[214:215], off
	s_setprio 1
	s_barrier
	s_waitcnt lgkmcnt(0)
	v_mfma_f32_16x16x32_bf16 v[120:123], v[190:193], v[148:151], v[120:123]
	v_mfma_f32_16x16x32_bf16 v[120:123], v[194:197], v[152:155], v[120:123]
	v_mfma_f32_16x16x32_bf16 v[104:107], v[194:197], v[160:163], v[104:107]
	v_mfma_f32_16x16x32_bf16 v[104:107], v[190:193], v[156:159], v[104:107]
	v_mfma_f32_16x16x32_bf16 v[88:91], v[190:193], v[164:167], v[88:91]
	v_mfma_f32_16x16x32_bf16 v[88:91], v[194:197], v[168:171], v[88:91]
	v_mfma_f32_16x16x32_bf16 v[72:75], v[194:197], v[186:189], v[72:75]
	v_mfma_f32_16x16x32_bf16 v[72:75], v[190:193], v[172:175], v[72:75]
	v_mfma_f32_16x16x32_bf16 v[68:71], v[204:207], v[172:175], v[68:71]
	v_mfma_f32_16x16x32_bf16 v[68:71], v[208:211], v[186:189], v[68:71]
	v_mfma_f32_16x16x32_bf16 v[84:87], v[208:211], v[168:171], v[84:87]
	v_mfma_f32_16x16x32_bf16 v[84:87], v[204:207], v[164:167], v[84:87]
	v_mfma_f32_16x16x32_bf16 v[100:103], v[204:207], v[156:159], v[100:103]
	v_mfma_f32_16x16x32_bf16 v[100:103], v[208:211], v[160:163], v[100:103]
	v_mfma_f32_16x16x32_bf16 v[116:119], v[208:211], v[152:155], v[116:119]
	s_setprio 0
	v_mfma_f32_16x16x32_bf16 v[116:119], v[204:207], v[148:151], v[116:119]
	s_barrier
	s_mov_b32 m0, s28
	v_lshl_add_u64 v[216:217], s[20:21], 0, v[180:181]
	ds_read_b128 v[148:151], v202 offset:16384
	ds_read_b128 v[152:155], v202 offset:17408
	ds_read_b128 v[156:159], v202 offset:18432
	ds_read_b128 v[160:163], v202 offset:19456
	ds_read_b128 v[164:167], v202 offset:20480
	ds_read_b128 v[168:171], v202 offset:21504
	ds_read_b128 v[172:175], v202 offset:22528
	ds_read_b128 v[186:189], v202 offset:23552
	global_load_lds_dwordx4 v[216:217], off
	v_lshl_add_u64 v[218:219], s[20:21], 0, v[178:179]
	s_mov_b32 m0, s29
	s_nop 0
	global_load_lds_dwordx4 v[218:219], off
	s_waitcnt vmcnt(10)
	s_setprio 1
	s_barrier
	s_waitcnt lgkmcnt(0)
	v_mfma_f32_16x16x32_bf16 v[64:67], v[132:135], v[148:151], v[64:67]
	v_mfma_f32_16x16x32_bf16 v[64:67], v[136:139], v[152:155], v[64:67]
	v_mfma_f32_16x16x32_bf16 v[48:51], v[136:139], v[160:163], v[48:51]
	v_mfma_f32_16x16x32_bf16 v[48:51], v[132:135], v[156:159], v[48:51]
	v_mfma_f32_16x16x32_bf16 v[32:35], v[132:135], v[164:167], v[32:35]
	v_mfma_f32_16x16x32_bf16 v[32:35], v[136:139], v[168:171], v[32:35]
	v_mfma_f32_16x16x32_bf16 v[16:19], v[136:139], v[186:189], v[16:19]
	v_mfma_f32_16x16x32_bf16 v[16:19], v[132:135], v[172:175], v[16:19]
	v_mfma_f32_16x16x32_bf16 v[12:15], v[140:143], v[172:175], v[12:15]
	v_mfma_f32_16x16x32_bf16 v[12:15], v[144:147], v[186:189], v[12:15]
	v_mfma_f32_16x16x32_bf16 v[28:31], v[144:147], v[168:171], v[28:31]
	v_mfma_f32_16x16x32_bf16 v[28:31], v[140:143], v[164:167], v[28:31]
	v_mfma_f32_16x16x32_bf16 v[44:47], v[140:143], v[156:159], v[44:47]
	v_mfma_f32_16x16x32_bf16 v[44:47], v[144:147], v[160:163], v[44:47]
	v_mfma_f32_16x16x32_bf16 v[60:63], v[144:147], v[152:155], v[60:63]
	s_setprio 0
	v_mfma_f32_16x16x32_bf16 v[60:63], v[140:143], v[148:151], v[60:63]
	s_barrier
	s_add_u32 s14, s18, 0x160000
	s_addc_u32 s15, s19, 0
	s_add_i32 s45, s46, s27
	v_lshl_add_u64 v[132:133], s[14:15], 0, v[2:3]
	s_mov_b32 m0, s45
	s_nop 0
	global_load_lds_dwordx4 v[132:133], off
	v_lshl_add_u64 v[132:133], s[14:15], 0, v[176:177]
	s_add_i32 m0, s45, 0x2000
	s_nop 0
	global_load_lds_dwordx4 v[132:133], off
	s_add_i32 s45, 0, 0x18000
	v_add_u32_e32 v144, s45, v200
	ds_read_b128 v[132:135], v144
	ds_read_b128 v[136:139], v144 offset:1024
	ds_read_b128 v[140:143], v144 offset:2048
	ds_read_b128 v[144:147], v144 offset:3072
	s_waitcnt vmcnt(6)
	s_setprio 1
	s_barrier
	v_mfma_f32_16x16x32_bf16 v[56:59], v[190:193], v[148:151], v[56:59]
	v_mfma_f32_16x16x32_bf16 v[56:59], v[194:197], v[152:155], v[56:59]
	v_mfma_f32_16x16x32_bf16 v[40:43], v[194:197], v[160:163], v[40:43]
	v_mfma_f32_16x16x32_bf16 v[40:43], v[190:193], v[156:159], v[40:43]
	v_mfma_f32_16x16x32_bf16 v[24:27], v[190:193], v[164:167], v[24:27]
	v_mfma_f32_16x16x32_bf16 v[24:27], v[194:197], v[168:171], v[24:27]
	v_mfma_f32_16x16x32_bf16 v[8:11], v[194:197], v[186:189], v[8:11]
	v_mfma_f32_16x16x32_bf16 v[8:11], v[190:193], v[172:175], v[8:11]
	v_mfma_f32_16x16x32_bf16 v[4:7], v[204:207], v[172:175], v[4:7]
	v_mfma_f32_16x16x32_bf16 v[4:7], v[208:211], v[186:189], v[4:7]
	v_mfma_f32_16x16x32_bf16 v[20:23], v[208:211], v[168:171], v[20:23]
	v_mfma_f32_16x16x32_bf16 v[20:23], v[204:207], v[164:167], v[20:23]
	v_mfma_f32_16x16x32_bf16 v[36:39], v[204:207], v[156:159], v[36:39]
	v_mfma_f32_16x16x32_bf16 v[36:39], v[208:211], v[160:163], v[36:39]
	v_mfma_f32_16x16x32_bf16 v[52:55], v[208:211], v[152:155], v[52:55]
	s_setprio 0
	v_mfma_f32_16x16x32_bf16 v[52:55], v[204:207], v[148:151], v[52:55]
	s_barrier
	s_add_u32 s14, s20, 0x160000
	s_addc_u32 s15, s21, 0
	s_mov_b32 m0, s30
	ds_read_b128 v[148:151], v202 offset:32768
	ds_read_b128 v[152:155], v202 offset:33792
	ds_read_b128 v[156:159], v202 offset:34816
	ds_read_b128 v[160:163], v202 offset:35840
	ds_read_b128 v[164:167], v202 offset:36864
	ds_read_b128 v[168:171], v202 offset:37888
	ds_read_b128 v[172:175], v202 offset:38912
	ds_read_b128 v[186:189], v202 offset:39936
	global_load_lds_dwordx4 v180, s[14:15]
	s_mov_b32 m0, s31
	s_nop 0
	global_load_lds_dwordx4 v178, s[14:15]
	s_waitcnt lgkmcnt(8)
	s_setprio 1
	s_barrier
	s_waitcnt lgkmcnt(0)
	v_mfma_f32_16x16x32_bf16 v[128:131], v[132:135], v[148:151], v[128:131]
	v_mfma_f32_16x16x32_bf16 v[128:131], v[136:139], v[152:155], v[128:131]
	v_mfma_f32_16x16x32_bf16 v[112:115], v[136:139], v[160:163], v[112:115]
	v_mfma_f32_16x16x32_bf16 v[112:115], v[132:135], v[156:159], v[112:115]
	v_mfma_f32_16x16x32_bf16 v[96:99], v[132:135], v[164:167], v[96:99]
	v_mfma_f32_16x16x32_bf16 v[96:99], v[136:139], v[168:171], v[96:99]
	v_mfma_f32_16x16x32_bf16 v[80:83], v[136:139], v[186:189], v[80:83]
	v_mfma_f32_16x16x32_bf16 v[80:83], v[132:135], v[172:175], v[80:83]
	v_mfma_f32_16x16x32_bf16 v[76:79], v[140:143], v[172:175], v[76:79]
	v_mfma_f32_16x16x32_bf16 v[76:79], v[144:147], v[186:189], v[76:79]
	v_mfma_f32_16x16x32_bf16 v[92:95], v[144:147], v[168:171], v[92:95]
	v_mfma_f32_16x16x32_bf16 v[92:95], v[140:143], v[164:167], v[92:95]
	v_mfma_f32_16x16x32_bf16 v[108:111], v[140:143], v[156:159], v[108:111]
	v_mfma_f32_16x16x32_bf16 v[108:111], v[144:147], v[160:163], v[108:111]
	v_mfma_f32_16x16x32_bf16 v[124:127], v[144:147], v[152:155], v[124:127]
	s_setprio 0
	v_mfma_f32_16x16x32_bf16 v[124:127], v[140:143], v[148:151], v[124:127]
	s_barrier
	s_add_i32 s20, 0, 0x1c000
	s_add_i32 s14, s45, s27
	v_add_u32_e32 v203, s20, v200
	v_lshl_add_u64 v[212:213], v[212:213], 0, s[2:3]
	s_mov_b32 m0, s14
	ds_read_b128 v[190:193], v203
	ds_read_b128 v[194:197], v203 offset:1024
	ds_read_b128 v[204:207], v203 offset:2048
	ds_read_b128 v[208:211], v203 offset:3072
	global_load_lds_dwordx4 v[212:213], off
	v_lshl_add_u64 v[212:213], v[214:215], 0, s[2:3]
	s_add_i32 m0, s14, 0x2000
	s_nop 0
	global_load_lds_dwordx4 v[212:213], off
	s_setprio 1
	s_barrier
	s_waitcnt lgkmcnt(0)
	v_mfma_f32_16x16x32_bf16 v[120:123], v[190:193], v[148:151], v[120:123]
	v_mfma_f32_16x16x32_bf16 v[120:123], v[194:197], v[152:155], v[120:123]
	v_mfma_f32_16x16x32_bf16 v[104:107], v[194:197], v[160:163], v[104:107]
	v_mfma_f32_16x16x32_bf16 v[104:107], v[190:193], v[156:159], v[104:107]
	v_mfma_f32_16x16x32_bf16 v[88:91], v[190:193], v[164:167], v[88:91]
	v_mfma_f32_16x16x32_bf16 v[88:91], v[194:197], v[168:171], v[88:91]
	v_mfma_f32_16x16x32_bf16 v[72:75], v[194:197], v[186:189], v[72:75]
	v_mfma_f32_16x16x32_bf16 v[72:75], v[190:193], v[172:175], v[72:75]
	v_mfma_f32_16x16x32_bf16 v[68:71], v[204:207], v[172:175], v[68:71]
	v_mfma_f32_16x16x32_bf16 v[68:71], v[208:211], v[186:189], v[68:71]
	v_mfma_f32_16x16x32_bf16 v[84:87], v[208:211], v[168:171], v[84:87]
	v_mfma_f32_16x16x32_bf16 v[84:87], v[204:207], v[164:167], v[84:87]
	v_mfma_f32_16x16x32_bf16 v[100:103], v[204:207], v[156:159], v[100:103]
	v_mfma_f32_16x16x32_bf16 v[100:103], v[208:211], v[160:163], v[100:103]
	v_mfma_f32_16x16x32_bf16 v[116:119], v[208:211], v[152:155], v[116:119]
	s_setprio 0
	v_mfma_f32_16x16x32_bf16 v[116:119], v[204:207], v[148:151], v[116:119]
	s_barrier
	s_mov_b32 m0, s36
	v_lshl_add_u64 v[212:213], v[216:217], 0, s[2:3]
	ds_read_b128 v[148:151], v202 offset:49152
	ds_read_b128 v[152:155], v202 offset:50176
	ds_read_b128 v[156:159], v202 offset:51200
	ds_read_b128 v[160:163], v202 offset:52224
	ds_read_b128 v[164:167], v202 offset:53248
	ds_read_b128 v[168:171], v202 offset:54272
	ds_read_b128 v[172:175], v202 offset:55296
	ds_read_b128 v[186:189], v202 offset:56320
	global_load_lds_dwordx4 v[212:213], off
	v_lshl_add_u64 v[212:213], v[218:219], 0, s[2:3]
	s_mov_b32 m0, s37
	s_nop 0
	global_load_lds_dwordx4 v[212:213], off
	s_setprio 1
	s_barrier
	s_waitcnt lgkmcnt(0)
	v_mfma_f32_16x16x32_bf16 v[64:67], v[132:135], v[148:151], v[64:67]
	v_mfma_f32_16x16x32_bf16 v[64:67], v[136:139], v[152:155], v[64:67]
	v_mfma_f32_16x16x32_bf16 v[48:51], v[136:139], v[160:163], v[48:51]
	v_mfma_f32_16x16x32_bf16 v[48:51], v[132:135], v[156:159], v[48:51]
	v_mfma_f32_16x16x32_bf16 v[32:35], v[132:135], v[164:167], v[32:35]
	v_mfma_f32_16x16x32_bf16 v[32:35], v[136:139], v[168:171], v[32:35]
	v_mfma_f32_16x16x32_bf16 v[16:19], v[136:139], v[186:189], v[16:19]
	v_mfma_f32_16x16x32_bf16 v[16:19], v[132:135], v[172:175], v[16:19]
	v_mfma_f32_16x16x32_bf16 v[12:15], v[140:143], v[172:175], v[12:15]
	v_mfma_f32_16x16x32_bf16 v[12:15], v[144:147], v[186:189], v[12:15]
	v_mfma_f32_16x16x32_bf16 v[28:31], v[144:147], v[168:171], v[28:31]
	v_mfma_f32_16x16x32_bf16 v[28:31], v[140:143], v[164:167], v[28:31]
	v_mfma_f32_16x16x32_bf16 v[44:47], v[140:143], v[156:159], v[44:47]
	v_mfma_f32_16x16x32_bf16 v[44:47], v[144:147], v[160:163], v[44:47]
	v_mfma_f32_16x16x32_bf16 v[60:63], v[144:147], v[152:155], v[60:63]
	s_setprio 0
	v_mfma_f32_16x16x32_bf16 v[60:63], v[140:143], v[148:151], v[60:63]
	s_barrier
	s_add_u32 s14, s18, 0x160080
	s_addc_u32 s15, s19, 0
	s_add_i32 s18, s20, s27
	v_lshl_add_u64 v[132:133], s[14:15], 0, v[2:3]
	s_mov_b32 m0, s18
	s_nop 0
	global_load_lds_dwordx4 v[132:133], off
	v_lshl_add_u64 v[132:133], s[14:15], 0, v[176:177]
	s_add_i32 m0, s18, 0x2000
	s_nop 0
	global_load_lds_dwordx4 v[132:133], off
	s_waitcnt vmcnt(6)
	s_setprio 1
	s_barrier
	v_mfma_f32_16x16x32_bf16 v[56:59], v[190:193], v[148:151], v[56:59]
	v_mfma_f32_16x16x32_bf16 v[56:59], v[194:197], v[152:155], v[56:59]
	v_mfma_f32_16x16x32_bf16 v[40:43], v[194:197], v[160:163], v[40:43]
	v_mfma_f32_16x16x32_bf16 v[40:43], v[190:193], v[156:159], v[40:43]
	v_mfma_f32_16x16x32_bf16 v[24:27], v[190:193], v[164:167], v[24:27]
	v_mfma_f32_16x16x32_bf16 v[24:27], v[194:197], v[168:171], v[24:27]
	v_mfma_f32_16x16x32_bf16 v[8:11], v[194:197], v[186:189], v[8:11]
	v_mfma_f32_16x16x32_bf16 v[8:11], v[190:193], v[172:175], v[8:11]
	v_mfma_f32_16x16x32_bf16 v[4:7], v[204:207], v[172:175], v[4:7]
	v_mfma_f32_16x16x32_bf16 v[4:7], v[208:211], v[186:189], v[4:7]
	v_mfma_f32_16x16x32_bf16 v[20:23], v[208:211], v[168:171], v[20:23]
	v_mfma_f32_16x16x32_bf16 v[20:23], v[204:207], v[164:167], v[20:23]
	v_mfma_f32_16x16x32_bf16 v[36:39], v[204:207], v[156:159], v[36:39]
	v_mfma_f32_16x16x32_bf16 v[36:39], v[208:211], v[160:163], v[36:39]
	v_mfma_f32_16x16x32_bf16 v[52:55], v[208:211], v[152:155], v[52:55]
	s_setprio 0
	v_mfma_f32_16x16x32_bf16 v[52:55], v[204:207], v[148:151], v[52:55]
	s_barrier
	s_add_i32 s44, s44, 2
	s_add_u32 s42, s42, 0x100
	s_addc_u32 s43, s43, 0
	s_cmpk_gt_u32 s44, 0x55
	s_mov_b64 s[14:15], s[16:17]
	s_cbranch_scc0 .LBB0_1180
	s_cmp_lt_i32 s41, 32
	s_mov_b64 s[14:15], 0
	s_cbranch_scc1 .LBB0_1183
	s_sub_i32 s14, s41, 32
	s_lshr_b32 s14, s14, 4
	s_add_i32 s14, s14, 1
	s_mul_hi_u32 s15, s14, 0x3000
	s_mulk_i32 s14, 0x3000
